# GEMM K-loops: per-phase s_setprio flips removed, one static s_setprio 1 for the younger wave half (waves 4-7) per tile, reset at loop exit
# speedup vs baseline: 1.0162x; 1.0162x over previous
.LBB0_130:
	s_ashr_i32 s13, s12, 31
	v_cmp_lt_i64_e32 vcc, s[14:15], v[140:141]
	s_lshl_b64 s[14:15], s[12:13], 19
	s_add_u32 s14, s39, s14
	s_addc_u32 s15, s40, s15
	s_and_b64 s[16:17], vcc, exec
	s_cselect_b32 s13, s15, s21
	s_cselect_b32 s53, s14, s20
	s_ashr_i32 s11, s10, 31
	s_lshl_b64 s[16:17], s[10:11], 19
	s_add_u32 s16, s33, s16
	s_addc_u32 s17, s34, s17
	s_and_b64 s[28:29], vcc, exec
	s_cselect_b32 s11, s17, s27
	s_cselect_b32 s54, s16, s26
	s_add_u32 s20, s20, 0x40080
	s_addc_u32 s21, s21, 0
	s_add_u32 s55, s26, 0x100
	s_addc_u32 s56, s27, 0
	s_mov_b32 s57, -2
	s_cmpk_lt_u32 s37, 0x100
	s_cbranch_scc1 .Lg131_noy
	s_setprio 1
	s_barrier
.Lg131_noy:
	ds_read_b128 v[152:155], v149
	ds_read_b128 v[156:159], v149 offset:1024
	ds_read_b128 v[160:163], v149 offset:2048
	ds_read_b128 v[164:167], v149 offset:3072
	s_add_u32 s26, s20, 0xfffc0080
	s_addc_u32 s27, s21, -1
	s_cmp_eq_u32 s57, 12
	s_cselect_b32 s29, s13, s27
	s_cselect_b32 s28, s53, s26
	s_cselect_b32 s27, s11, s56
	s_cselect_b32 s26, s54, s55
	s_add_i32 m0, s19, 0xc000
	ds_read_b128 v[168:171], v150
	ds_read_b128 v[172:175], v150 offset:1024
	ds_read_b128 v[176:179], v150 offset:2048
	ds_read_b128 v[180:183], v150 offset:3072
	ds_read_b128 v[184:187], v150 offset:4096
	ds_read_b128 v[188:191], v150 offset:5120
	ds_read_b128 v[192:195], v150 offset:6144
	ds_read_b128 v[196:199], v150 offset:7168
	global_load_lds_dwordx4 v136, s[20:21]
	s_add_i32 m0, s19, 0xe000
	s_nop 0
	global_load_lds_dwordx4 v138, s[20:21]
	s_waitcnt lgkmcnt(8)
	s_barrier
	s_waitcnt lgkmcnt(0)
	s_waitcnt lgkmcnt(0)
	v_mfma_f32_16x16x32_bf16 v[124:127], v[152:155], v[168:171], 0
	v_mfma_f32_16x16x32_bf16 v[120:123], v[160:163], v[168:171], 0
	v_mfma_f32_16x16x32_bf16 v[108:111], v[152:155], v[176:179], 0
	v_mfma_f32_16x16x32_bf16 v[104:107], v[160:163], v[176:179], 0
	v_mfma_f32_16x16x32_bf16 v[92:95], v[152:155], v[184:187], 0
	v_mfma_f32_16x16x32_bf16 v[88:91], v[160:163], v[184:187], 0
	v_mfma_f32_16x16x32_bf16 v[76:79], v[152:155], v[192:195], 0
	v_mfma_f32_16x16x32_bf16 v[72:75], v[160:163], v[192:195], 0
	v_mfma_f32_16x16x32_bf16 v[124:127], v[156:159], v[172:175], v[124:127]
	v_mfma_f32_16x16x32_bf16 v[120:123], v[164:167], v[172:175], v[120:123]
	v_mfma_f32_16x16x32_bf16 v[108:111], v[156:159], v[180:183], v[108:111]
	v_mfma_f32_16x16x32_bf16 v[104:107], v[164:167], v[180:183], v[104:107]
	v_mfma_f32_16x16x32_bf16 v[92:95], v[156:159], v[188:191], v[92:95]
	v_mfma_f32_16x16x32_bf16 v[88:91], v[164:167], v[188:191], v[88:91]
	v_mfma_f32_16x16x32_bf16 v[76:79], v[156:159], v[196:199], v[76:79]
	v_mfma_f32_16x16x32_bf16 v[72:75], v[164:167], v[196:199], v[72:75]
	s_barrier
	s_add_i32 s58, s47, s38
	s_add_u32 s80, s26, 0x80
	s_addc_u32 s81, s27, 0
	s_mov_b32 m0, s58
	ds_read_b128 v[200:203], v151
	ds_read_b128 v[204:207], v151 offset:1024
	ds_read_b128 v[208:211], v151 offset:2048
	ds_read_b128 v[212:215], v151 offset:3072
	global_load_lds_dwordx4 v132, s[26:27]
	s_add_i32 m0, s58, 0x2000
	s_nop 0
	global_load_lds_dwordx4 v128, s[26:27]
	s_waitcnt vmcnt(10)
	s_barrier
	s_waitcnt lgkmcnt(0)
	s_waitcnt lgkmcnt(0)
	v_mfma_f32_16x16x32_bf16 v[116:119], v[200:203], v[168:171], 0
	v_mfma_f32_16x16x32_bf16 v[112:115], v[208:211], v[168:171], 0
	v_mfma_f32_16x16x32_bf16 v[100:103], v[200:203], v[176:179], 0
	v_mfma_f32_16x16x32_bf16 v[96:99], v[208:211], v[176:179], 0
	v_mfma_f32_16x16x32_bf16 v[84:87], v[200:203], v[184:187], 0
	v_mfma_f32_16x16x32_bf16 v[80:83], v[208:211], v[184:187], 0
	v_mfma_f32_16x16x32_bf16 v[68:71], v[200:203], v[192:195], 0
	v_mfma_f32_16x16x32_bf16 v[64:67], v[208:211], v[192:195], 0
	v_mfma_f32_16x16x32_bf16 v[116:119], v[204:207], v[172:175], v[116:119]
	v_mfma_f32_16x16x32_bf16 v[112:115], v[212:215], v[172:175], v[112:115]
	v_mfma_f32_16x16x32_bf16 v[100:103], v[204:207], v[180:183], v[100:103]
	v_mfma_f32_16x16x32_bf16 v[96:99], v[212:215], v[180:183], v[96:99]
	v_mfma_f32_16x16x32_bf16 v[84:87], v[204:207], v[188:191], v[84:87]
	v_mfma_f32_16x16x32_bf16 v[80:83], v[212:215], v[188:191], v[80:83]
	v_mfma_f32_16x16x32_bf16 v[68:71], v[204:207], v[196:199], v[68:71]
	v_mfma_f32_16x16x32_bf16 v[64:67], v[212:215], v[196:199], v[64:67]
	s_mov_b32 m0, s19
	s_add_u32 s82, s28, 0x80
	s_addc_u32 s83, s29, 0
	s_barrier
	ds_read_b128 v[168:171], v150 offset:16384
	ds_read_b128 v[172:175], v150 offset:17408
	ds_read_b128 v[176:179], v150 offset:18432
	ds_read_b128 v[180:183], v150 offset:19456
	ds_read_b128 v[184:187], v150 offset:20480
	ds_read_b128 v[188:191], v150 offset:21504
	ds_read_b128 v[192:195], v150 offset:22528
	ds_read_b128 v[196:199], v150 offset:23552
	global_load_lds_dwordx4 v134, s[28:29]
	s_mov_b32 m0, s42
	s_nop 0
	global_load_lds_dwordx4 v130, s[28:29]
	s_barrier
	s_waitcnt lgkmcnt(0)
	s_waitcnt lgkmcnt(0)
	v_mfma_f32_16x16x32_bf16 v[60:63], v[152:155], v[168:171], 0
	v_mfma_f32_16x16x32_bf16 v[56:59], v[160:163], v[168:171], 0
	v_mfma_f32_16x16x32_bf16 v[44:47], v[152:155], v[176:179], 0
	v_mfma_f32_16x16x32_bf16 v[40:43], v[160:163], v[176:179], 0
	v_mfma_f32_16x16x32_bf16 v[28:31], v[152:155], v[184:187], 0
	v_mfma_f32_16x16x32_bf16 v[24:27], v[160:163], v[184:187], 0
	v_mfma_f32_16x16x32_bf16 v[12:15], v[152:155], v[192:195], 0
	v_mfma_f32_16x16x32_bf16 v[8:11], v[160:163], v[192:195], 0
	v_mfma_f32_16x16x32_bf16 v[60:63], v[156:159], v[172:175], v[60:63]
	v_mfma_f32_16x16x32_bf16 v[56:59], v[164:167], v[172:175], v[56:59]
	v_mfma_f32_16x16x32_bf16 v[44:47], v[156:159], v[180:183], v[44:47]
	v_mfma_f32_16x16x32_bf16 v[40:43], v[164:167], v[180:183], v[40:43]
	v_mfma_f32_16x16x32_bf16 v[28:31], v[156:159], v[188:191], v[28:31]
	v_mfma_f32_16x16x32_bf16 v[24:27], v[164:167], v[188:191], v[24:27]
	v_mfma_f32_16x16x32_bf16 v[12:15], v[156:159], v[196:199], v[12:15]
	v_mfma_f32_16x16x32_bf16 v[8:11], v[164:167], v[196:199], v[8:11]
	s_barrier
	s_add_u32 s58, s26, 0x40000
	s_addc_u32 s59, s27, 0
	s_add_i32 s60, s48, s38
	s_mov_b32 m0, s60
	s_nop 0
	global_load_lds_dwordx4 v132, s[58:59]
	s_add_i32 m0, s60, 0x2000
	s_nop 0
	global_load_lds_dwordx4 v128, s[58:59]
	s_waitcnt vmcnt(8)
	s_barrier
	v_mfma_f32_16x16x32_bf16 v[52:55], v[200:203], v[168:171], 0
	v_mfma_f32_16x16x32_bf16 v[48:51], v[208:211], v[168:171], 0
	v_mfma_f32_16x16x32_bf16 v[36:39], v[200:203], v[176:179], 0
	v_mfma_f32_16x16x32_bf16 v[32:35], v[208:211], v[176:179], 0
	v_mfma_f32_16x16x32_bf16 v[20:23], v[200:203], v[184:187], 0
	v_mfma_f32_16x16x32_bf16 v[16:19], v[208:211], v[184:187], 0
	v_mfma_f32_16x16x32_bf16 v[4:7], v[200:203], v[192:195], 0
	v_mfma_f32_16x16x32_bf16 v[0:3], v[208:211], v[192:195], 0
	v_mfma_f32_16x16x32_bf16 v[52:55], v[204:207], v[172:175], v[52:55]
	v_mfma_f32_16x16x32_bf16 v[48:51], v[212:215], v[172:175], v[48:51]
	v_mfma_f32_16x16x32_bf16 v[36:39], v[204:207], v[180:183], v[36:39]
	v_mfma_f32_16x16x32_bf16 v[32:35], v[212:215], v[180:183], v[32:35]
	v_mfma_f32_16x16x32_bf16 v[20:23], v[204:207], v[188:191], v[20:23]
	v_mfma_f32_16x16x32_bf16 v[16:19], v[212:215], v[188:191], v[16:19]
	v_mfma_f32_16x16x32_bf16 v[4:7], v[204:207], v[196:199], v[4:7]
	v_mfma_f32_16x16x32_bf16 v[0:3], v[212:215], v[196:199], v[0:3]
	s_add_i32 s58, 0, 0x18000
	v_add_u32_e32 v164, s58, v145
	s_barrier
	s_branch .Lg131_mid
.LBB0_131:
	ds_read_b128 v[152:155], v149
	ds_read_b128 v[156:159], v149 offset:1024
	ds_read_b128 v[160:163], v149 offset:2048
	ds_read_b128 v[164:167], v149 offset:3072
	s_add_u32 s26, s20, 0xfffc0080
	s_addc_u32 s27, s21, -1
	s_cmp_eq_u32 s57, 12
	s_cselect_b32 s29, s13, s27
	s_cselect_b32 s28, s53, s26
	s_cselect_b32 s27, s11, s56
	s_cselect_b32 s26, s54, s55
	s_add_i32 m0, s19, 0xc000
	ds_read_b128 v[168:171], v150
	ds_read_b128 v[172:175], v150 offset:1024
	ds_read_b128 v[176:179], v150 offset:2048
	ds_read_b128 v[180:183], v150 offset:3072
	ds_read_b128 v[184:187], v150 offset:4096
	ds_read_b128 v[188:191], v150 offset:5120
	ds_read_b128 v[192:195], v150 offset:6144
	ds_read_b128 v[196:199], v150 offset:7168
	global_load_lds_dwordx4 v136, s[20:21]
	s_add_i32 m0, s19, 0xe000
	s_nop 0
	global_load_lds_dwordx4 v138, s[20:21]
	s_waitcnt lgkmcnt(8)
	s_barrier
	s_waitcnt lgkmcnt(0)
	s_waitcnt lgkmcnt(0)
	v_mfma_f32_16x16x32_bf16 v[124:127], v[152:155], v[168:171], v[124:127]
	v_mfma_f32_16x16x32_bf16 v[120:123], v[160:163], v[168:171], v[120:123]
	v_mfma_f32_16x16x32_bf16 v[108:111], v[152:155], v[176:179], v[108:111]
	v_mfma_f32_16x16x32_bf16 v[104:107], v[160:163], v[176:179], v[104:107]
	v_mfma_f32_16x16x32_bf16 v[92:95], v[152:155], v[184:187], v[92:95]
	v_mfma_f32_16x16x32_bf16 v[88:91], v[160:163], v[184:187], v[88:91]
	v_mfma_f32_16x16x32_bf16 v[76:79], v[152:155], v[192:195], v[76:79]
	v_mfma_f32_16x16x32_bf16 v[72:75], v[160:163], v[192:195], v[72:75]
	v_mfma_f32_16x16x32_bf16 v[124:127], v[156:159], v[172:175], v[124:127]
	v_mfma_f32_16x16x32_bf16 v[120:123], v[164:167], v[172:175], v[120:123]
	v_mfma_f32_16x16x32_bf16 v[108:111], v[156:159], v[180:183], v[108:111]
	v_mfma_f32_16x16x32_bf16 v[104:107], v[164:167], v[180:183], v[104:107]
	v_mfma_f32_16x16x32_bf16 v[92:95], v[156:159], v[188:191], v[92:95]
	v_mfma_f32_16x16x32_bf16 v[88:91], v[164:167], v[188:191], v[88:91]
	v_mfma_f32_16x16x32_bf16 v[76:79], v[156:159], v[196:199], v[76:79]
	v_mfma_f32_16x16x32_bf16 v[72:75], v[164:167], v[196:199], v[72:75]
	s_barrier
	s_add_i32 s58, s47, s38
	s_add_u32 s80, s26, 0x80
	s_addc_u32 s81, s27, 0
	s_mov_b32 m0, s58
	ds_read_b128 v[200:203], v151
	ds_read_b128 v[204:207], v151 offset:1024
	ds_read_b128 v[208:211], v151 offset:2048
	ds_read_b128 v[212:215], v151 offset:3072
	global_load_lds_dwordx4 v132, s[26:27]
	s_add_i32 m0, s58, 0x2000
	s_nop 0
	global_load_lds_dwordx4 v128, s[26:27]
	s_waitcnt vmcnt(10)
	s_barrier
	s_waitcnt lgkmcnt(0)
	s_waitcnt lgkmcnt(0)
	v_mfma_f32_16x16x32_bf16 v[116:119], v[200:203], v[168:171], v[116:119]
	v_mfma_f32_16x16x32_bf16 v[112:115], v[208:211], v[168:171], v[112:115]
	v_mfma_f32_16x16x32_bf16 v[100:103], v[200:203], v[176:179], v[100:103]
	v_mfma_f32_16x16x32_bf16 v[96:99], v[208:211], v[176:179], v[96:99]
	v_mfma_f32_16x16x32_bf16 v[84:87], v[200:203], v[184:187], v[84:87]
	v_mfma_f32_16x16x32_bf16 v[80:83], v[208:211], v[184:187], v[80:83]
	v_mfma_f32_16x16x32_bf16 v[68:71], v[200:203], v[192:195], v[68:71]
	v_mfma_f32_16x16x32_bf16 v[64:67], v[208:211], v[192:195], v[64:67]
	v_mfma_f32_16x16x32_bf16 v[116:119], v[204:207], v[172:175], v[116:119]
	v_mfma_f32_16x16x32_bf16 v[112:115], v[212:215], v[172:175], v[112:115]
	v_mfma_f32_16x16x32_bf16 v[100:103], v[204:207], v[180:183], v[100:103]
	v_mfma_f32_16x16x32_bf16 v[96:99], v[212:215], v[180:183], v[96:99]
	v_mfma_f32_16x16x32_bf16 v[84:87], v[204:207], v[188:191], v[84:87]
	v_mfma_f32_16x16x32_bf16 v[80:83], v[212:215], v[188:191], v[80:83]
	v_mfma_f32_16x16x32_bf16 v[68:71], v[204:207], v[196:199], v[68:71]
	v_mfma_f32_16x16x32_bf16 v[64:67], v[212:215], v[196:199], v[64:67]
	s_mov_b32 m0, s19
	s_add_u32 s82, s28, 0x80
	s_addc_u32 s83, s29, 0
	s_barrier
	ds_read_b128 v[168:171], v150 offset:16384
	ds_read_b128 v[172:175], v150 offset:17408
	ds_read_b128 v[176:179], v150 offset:18432
	ds_read_b128 v[180:183], v150 offset:19456
	ds_read_b128 v[184:187], v150 offset:20480
	ds_read_b128 v[188:191], v150 offset:21504
	ds_read_b128 v[192:195], v150 offset:22528
	ds_read_b128 v[196:199], v150 offset:23552
	global_load_lds_dwordx4 v134, s[28:29]
	s_mov_b32 m0, s42
	s_nop 0
	global_load_lds_dwordx4 v130, s[28:29]
	s_barrier
	s_waitcnt lgkmcnt(0)
	s_waitcnt lgkmcnt(0)
	v_mfma_f32_16x16x32_bf16 v[60:63], v[152:155], v[168:171], v[60:63]
	v_mfma_f32_16x16x32_bf16 v[56:59], v[160:163], v[168:171], v[56:59]
	v_mfma_f32_16x16x32_bf16 v[44:47], v[152:155], v[176:179], v[44:47]
	v_mfma_f32_16x16x32_bf16 v[40:43], v[160:163], v[176:179], v[40:43]
	v_mfma_f32_16x16x32_bf16 v[28:31], v[152:155], v[184:187], v[28:31]
	v_mfma_f32_16x16x32_bf16 v[24:27], v[160:163], v[184:187], v[24:27]
	v_mfma_f32_16x16x32_bf16 v[12:15], v[152:155], v[192:195], v[12:15]
	v_mfma_f32_16x16x32_bf16 v[8:11], v[160:163], v[192:195], v[8:11]
	v_mfma_f32_16x16x32_bf16 v[60:63], v[156:159], v[172:175], v[60:63]
	v_mfma_f32_16x16x32_bf16 v[56:59], v[164:167], v[172:175], v[56:59]
	v_mfma_f32_16x16x32_bf16 v[44:47], v[156:159], v[180:183], v[44:47]
	v_mfma_f32_16x16x32_bf16 v[40:43], v[164:167], v[180:183], v[40:43]
	v_mfma_f32_16x16x32_bf16 v[28:31], v[156:159], v[188:191], v[28:31]
	v_mfma_f32_16x16x32_bf16 v[24:27], v[164:167], v[188:191], v[24:27]
	v_mfma_f32_16x16x32_bf16 v[12:15], v[156:159], v[196:199], v[12:15]
	v_mfma_f32_16x16x32_bf16 v[8:11], v[164:167], v[196:199], v[8:11]
	s_barrier
	s_add_u32 s58, s26, 0x40000
	s_addc_u32 s59, s27, 0
	s_add_i32 s60, s48, s38
	s_mov_b32 m0, s60
	s_nop 0
	global_load_lds_dwordx4 v132, s[58:59]
	s_add_i32 m0, s60, 0x2000
	s_nop 0
	global_load_lds_dwordx4 v128, s[58:59]
	s_waitcnt vmcnt(8)
	s_barrier
	v_mfma_f32_16x16x32_bf16 v[52:55], v[200:203], v[168:171], v[52:55]
	v_mfma_f32_16x16x32_bf16 v[48:51], v[208:211], v[168:171], v[48:51]
	v_mfma_f32_16x16x32_bf16 v[36:39], v[200:203], v[176:179], v[36:39]
	v_mfma_f32_16x16x32_bf16 v[32:35], v[208:211], v[176:179], v[32:35]
	v_mfma_f32_16x16x32_bf16 v[20:23], v[200:203], v[184:187], v[20:23]
	v_mfma_f32_16x16x32_bf16 v[16:19], v[208:211], v[184:187], v[16:19]
	v_mfma_f32_16x16x32_bf16 v[4:7], v[200:203], v[192:195], v[4:7]
	v_mfma_f32_16x16x32_bf16 v[0:3], v[208:211], v[192:195], v[0:3]
	v_mfma_f32_16x16x32_bf16 v[52:55], v[204:207], v[172:175], v[52:55]
	v_mfma_f32_16x16x32_bf16 v[48:51], v[212:215], v[172:175], v[48:51]
	v_mfma_f32_16x16x32_bf16 v[36:39], v[204:207], v[180:183], v[36:39]
	v_mfma_f32_16x16x32_bf16 v[32:35], v[212:215], v[180:183], v[32:35]
	v_mfma_f32_16x16x32_bf16 v[20:23], v[204:207], v[188:191], v[20:23]
	v_mfma_f32_16x16x32_bf16 v[16:19], v[212:215], v[188:191], v[16:19]
	v_mfma_f32_16x16x32_bf16 v[4:7], v[204:207], v[196:199], v[4:7]
	v_mfma_f32_16x16x32_bf16 v[0:3], v[212:215], v[196:199], v[0:3]
	s_add_i32 s58, 0, 0x18000
	v_add_u32_e32 v164, s58, v145
	s_barrier
.Lg131_mid:
	ds_read_b128 v[152:155], v164
	ds_read_b128 v[156:159], v164 offset:1024
	ds_read_b128 v[160:163], v164 offset:2048
	ds_read_b128 v[164:167], v164 offset:3072
	s_add_u32 s28, s28, 0x40000
	s_addc_u32 s29, s29, 0
	s_mov_b32 m0, s43
	ds_read_b128 v[168:171], v150 offset:32768
	ds_read_b128 v[172:175], v150 offset:33792
	ds_read_b128 v[176:179], v150 offset:34816
	ds_read_b128 v[180:183], v150 offset:35840
	ds_read_b128 v[184:187], v150 offset:36864
	ds_read_b128 v[188:191], v150 offset:37888
	ds_read_b128 v[192:195], v150 offset:38912
	ds_read_b128 v[196:199], v150 offset:39936
	global_load_lds_dwordx4 v134, s[28:29]
	s_mov_b32 m0, s44
	s_nop 0
	global_load_lds_dwordx4 v130, s[28:29]
	s_waitcnt lgkmcnt(8)
	s_barrier
	s_waitcnt lgkmcnt(0)
	s_waitcnt lgkmcnt(0)
	v_mfma_f32_16x16x32_bf16 v[124:127], v[152:155], v[168:171], v[124:127]
	v_mfma_f32_16x16x32_bf16 v[120:123], v[160:163], v[168:171], v[120:123]
	v_mfma_f32_16x16x32_bf16 v[108:111], v[152:155], v[176:179], v[108:111]
	v_mfma_f32_16x16x32_bf16 v[104:107], v[160:163], v[176:179], v[104:107]
	v_mfma_f32_16x16x32_bf16 v[92:95], v[152:155], v[184:187], v[92:95]
	v_mfma_f32_16x16x32_bf16 v[88:91], v[160:163], v[184:187], v[88:91]
	v_mfma_f32_16x16x32_bf16 v[76:79], v[152:155], v[192:195], v[76:79]
	v_mfma_f32_16x16x32_bf16 v[72:75], v[160:163], v[192:195], v[72:75]
	v_mfma_f32_16x16x32_bf16 v[124:127], v[156:159], v[172:175], v[124:127]
	v_mfma_f32_16x16x32_bf16 v[120:123], v[164:167], v[172:175], v[120:123]
	v_mfma_f32_16x16x32_bf16 v[108:111], v[156:159], v[180:183], v[108:111]
	v_mfma_f32_16x16x32_bf16 v[104:107], v[164:167], v[180:183], v[104:107]
	v_mfma_f32_16x16x32_bf16 v[92:95], v[156:159], v[188:191], v[92:95]
	v_mfma_f32_16x16x32_bf16 v[88:91], v[164:167], v[188:191], v[88:91]
	v_mfma_f32_16x16x32_bf16 v[76:79], v[156:159], v[196:199], v[76:79]
	v_mfma_f32_16x16x32_bf16 v[72:75], v[164:167], v[196:199], v[72:75]
	s_barrier
	s_add_i32 s28, 0, 0x1c000
	s_add_i32 s29, s58, s38
	v_add_u32_e32 v212, s28, v145
	s_mov_b32 m0, s29
	ds_read_b128 v[200:203], v212
	ds_read_b128 v[204:207], v212 offset:1024
	ds_read_b128 v[208:211], v212 offset:2048
	ds_read_b128 v[212:215], v212 offset:3072
	global_load_lds_dwordx4 v132, s[80:81]
	s_add_i32 m0, s29, 0x2000
	s_nop 0
	global_load_lds_dwordx4 v128, s[80:81]
	s_waitcnt vmcnt(10)
	s_barrier
	s_waitcnt lgkmcnt(0)
	s_waitcnt lgkmcnt(0)
	v_mfma_f32_16x16x32_bf16 v[116:119], v[200:203], v[168:171], v[116:119]
	v_mfma_f32_16x16x32_bf16 v[112:115], v[208:211], v[168:171], v[112:115]
	v_mfma_f32_16x16x32_bf16 v[100:103], v[200:203], v[176:179], v[100:103]
	v_mfma_f32_16x16x32_bf16 v[96:99], v[208:211], v[176:179], v[96:99]
	v_mfma_f32_16x16x32_bf16 v[84:87], v[200:203], v[184:187], v[84:87]
	v_mfma_f32_16x16x32_bf16 v[80:83], v[208:211], v[184:187], v[80:83]
	v_mfma_f32_16x16x32_bf16 v[68:71], v[200:203], v[192:195], v[68:71]
	v_mfma_f32_16x16x32_bf16 v[64:67], v[208:211], v[192:195], v[64:67]
	v_mfma_f32_16x16x32_bf16 v[116:119], v[204:207], v[172:175], v[116:119]
	v_mfma_f32_16x16x32_bf16 v[112:115], v[212:215], v[172:175], v[112:115]
	v_mfma_f32_16x16x32_bf16 v[100:103], v[204:207], v[180:183], v[100:103]
	v_mfma_f32_16x16x32_bf16 v[96:99], v[212:215], v[180:183], v[96:99]
	v_mfma_f32_16x16x32_bf16 v[84:87], v[204:207], v[188:191], v[84:87]
	v_mfma_f32_16x16x32_bf16 v[80:83], v[212:215], v[188:191], v[80:83]
	v_mfma_f32_16x16x32_bf16 v[68:71], v[204:207], v[196:199], v[68:71]
	v_mfma_f32_16x16x32_bf16 v[64:67], v[212:215], v[196:199], v[64:67]
	s_mov_b32 m0, s45
	s_barrier
	ds_read_b128 v[168:171], v150 offset:49152
	ds_read_b128 v[172:175], v150 offset:50176
	ds_read_b128 v[176:179], v150 offset:51200
	ds_read_b128 v[180:183], v150 offset:52224
	ds_read_b128 v[184:187], v150 offset:53248
	ds_read_b128 v[188:191], v150 offset:54272
	ds_read_b128 v[192:195], v150 offset:55296
	ds_read_b128 v[196:199], v150 offset:56320
	global_load_lds_dwordx4 v134, s[82:83]
	s_mov_b32 m0, s46
	s_nop 0
	global_load_lds_dwordx4 v130, s[82:83]
	s_barrier
	s_waitcnt lgkmcnt(0)
	s_waitcnt lgkmcnt(0)
	v_mfma_f32_16x16x32_bf16 v[60:63], v[152:155], v[168:171], v[60:63]
	v_mfma_f32_16x16x32_bf16 v[56:59], v[160:163], v[168:171], v[56:59]
	v_mfma_f32_16x16x32_bf16 v[44:47], v[152:155], v[176:179], v[44:47]
	v_mfma_f32_16x16x32_bf16 v[40:43], v[160:163], v[176:179], v[40:43]
	v_mfma_f32_16x16x32_bf16 v[28:31], v[152:155], v[184:187], v[28:31]
	v_mfma_f32_16x16x32_bf16 v[24:27], v[160:163], v[184:187], v[24:27]
	v_mfma_f32_16x16x32_bf16 v[12:15], v[152:155], v[192:195], v[12:15]
	v_mfma_f32_16x16x32_bf16 v[8:11], v[160:163], v[192:195], v[8:11]
	v_mfma_f32_16x16x32_bf16 v[60:63], v[156:159], v[172:175], v[60:63]
	v_mfma_f32_16x16x32_bf16 v[56:59], v[164:167], v[172:175], v[56:59]
	v_mfma_f32_16x16x32_bf16 v[44:47], v[156:159], v[180:183], v[44:47]
	v_mfma_f32_16x16x32_bf16 v[40:43], v[164:167], v[180:183], v[40:43]
	v_mfma_f32_16x16x32_bf16 v[28:31], v[156:159], v[188:191], v[28:31]
	v_mfma_f32_16x16x32_bf16 v[24:27], v[164:167], v[188:191], v[24:27]
	v_mfma_f32_16x16x32_bf16 v[12:15], v[156:159], v[196:199], v[12:15]
	v_mfma_f32_16x16x32_bf16 v[8:11], v[164:167], v[196:199], v[8:11]
	s_barrier
	s_add_u32 s26, s26, 0x40080
	s_addc_u32 s27, s27, 0
	s_add_i32 s28, s28, s38
	s_mov_b32 m0, s28
	s_nop 0
	global_load_lds_dwordx4 v132, s[26:27]
	s_add_i32 m0, s28, 0x2000
	s_nop 0
	global_load_lds_dwordx4 v128, s[26:27]
	s_waitcnt vmcnt(8)
	s_barrier
	v_mfma_f32_16x16x32_bf16 v[52:55], v[200:203], v[168:171], v[52:55]
	v_mfma_f32_16x16x32_bf16 v[48:51], v[208:211], v[168:171], v[48:51]
	v_mfma_f32_16x16x32_bf16 v[36:39], v[200:203], v[176:179], v[36:39]
	v_mfma_f32_16x16x32_bf16 v[32:35], v[208:211], v[176:179], v[32:35]
	v_mfma_f32_16x16x32_bf16 v[20:23], v[200:203], v[184:187], v[20:23]
	v_mfma_f32_16x16x32_bf16 v[16:19], v[208:211], v[184:187], v[16:19]
	v_mfma_f32_16x16x32_bf16 v[4:7], v[200:203], v[192:195], v[4:7]
	v_mfma_f32_16x16x32_bf16 v[0:3], v[208:211], v[192:195], v[0:3]
	v_mfma_f32_16x16x32_bf16 v[52:55], v[204:207], v[172:175], v[52:55]
	v_mfma_f32_16x16x32_bf16 v[48:51], v[212:215], v[172:175], v[48:51]
	v_mfma_f32_16x16x32_bf16 v[36:39], v[204:207], v[180:183], v[36:39]
	v_mfma_f32_16x16x32_bf16 v[32:35], v[212:215], v[180:183], v[32:35]
	v_mfma_f32_16x16x32_bf16 v[20:23], v[204:207], v[188:191], v[20:23]
	v_mfma_f32_16x16x32_bf16 v[16:19], v[212:215], v[188:191], v[16:19]
	v_mfma_f32_16x16x32_bf16 v[4:7], v[204:207], v[196:199], v[4:7]
	v_mfma_f32_16x16x32_bf16 v[0:3], v[212:215], v[196:199], v[0:3]
	s_add_i32 s57, s57, 2
	s_add_u32 s20, s20, 0x100
	s_addc_u32 s21, s21, 0
	s_add_u32 s55, s55, 0x100
	s_addc_u32 s56, s56, 0
	s_cmp_gt_u32 s57, 13
	s_barrier
	s_cbranch_scc0 .LBB0_131
	s_setprio 0
	s_cmpk_gt_u32 s37, 0xff
	s_cbranch_scc1 .Lg131_nox
	s_barrier

.LBB0_247:
	s_add_u32 s57, s26, 0x100
	s_addc_u32 s58, s27, 0
	s_mov_b32 s59, -2
	s_waitcnt lgkmcnt(0)
	s_cmpk_lt_u32 s35, 0x100
	s_cbranch_scc1 .Lg248_noy
	s_setprio 1
	s_barrier
.Lg248_noy:
	ds_read_b128 v[144:147], v151
	ds_read_b128 v[156:159], v151 offset:1024
	ds_read_b128 v[160:163], v151 offset:2048
	ds_read_b128 v[164:167], v151 offset:3072
	s_add_u32 s26, s20, 0x100
	s_addc_u32 s27, s21, 0
	s_cmp_eq_u32 s59, 40
	s_cselect_b32 s31, s9, s27
	s_cselect_b32 s30, s8, s26
	s_cselect_b32 s29, s11, s58
	s_cselect_b32 s28, s10, s57
	s_add_i32 m0, s41, 0xc000
	ds_read_b128 v[168:171], v152
	ds_read_b128 v[172:175], v152 offset:1024
	ds_read_b128 v[176:179], v152 offset:2048
	ds_read_b128 v[180:183], v152 offset:3072
	ds_read_b128 v[184:187], v152 offset:4096
	ds_read_b128 v[188:191], v152 offset:5120
	ds_read_b128 v[192:195], v152 offset:6144
	ds_read_b128 v[196:199], v152 offset:7168
	global_load_lds_dwordx4 v136, s[20:21]
	s_add_i32 m0, s41, 0xe000
	s_nop 0
	global_load_lds_dwordx4 v138, s[20:21]
	s_waitcnt lgkmcnt(8)
	s_barrier
	s_waitcnt lgkmcnt(0)
	s_waitcnt lgkmcnt(0)
	v_mfma_f32_16x16x32_bf16 v[124:127], v[144:147], v[168:171], 0
	v_mfma_f32_16x16x32_bf16 v[120:123], v[160:163], v[168:171], 0
	v_mfma_f32_16x16x32_bf16 v[108:111], v[144:147], v[176:179], 0
	v_mfma_f32_16x16x32_bf16 v[104:107], v[160:163], v[176:179], 0
	v_mfma_f32_16x16x32_bf16 v[92:95], v[144:147], v[184:187], 0
	v_mfma_f32_16x16x32_bf16 v[88:91], v[160:163], v[184:187], 0
	v_mfma_f32_16x16x32_bf16 v[76:79], v[144:147], v[192:195], 0
	v_mfma_f32_16x16x32_bf16 v[72:75], v[160:163], v[192:195], 0
	v_mfma_f32_16x16x32_bf16 v[124:127], v[156:159], v[172:175], v[124:127]
	v_mfma_f32_16x16x32_bf16 v[120:123], v[164:167], v[172:175], v[120:123]
	v_mfma_f32_16x16x32_bf16 v[108:111], v[156:159], v[180:183], v[108:111]
	v_mfma_f32_16x16x32_bf16 v[104:107], v[164:167], v[180:183], v[104:107]
	v_mfma_f32_16x16x32_bf16 v[92:95], v[156:159], v[188:191], v[92:95]
	v_mfma_f32_16x16x32_bf16 v[88:91], v[164:167], v[188:191], v[88:91]
	v_mfma_f32_16x16x32_bf16 v[76:79], v[156:159], v[196:199], v[76:79]
	v_mfma_f32_16x16x32_bf16 v[72:75], v[164:167], v[196:199], v[72:75]
	s_barrier
	s_add_i32 s20, s51, s40
	s_add_u32 s80, s28, 0x80
	s_addc_u32 s81, s29, 0
	s_mov_b32 m0, s20
	ds_read_b128 v[200:203], v153
	ds_read_b128 v[204:207], v153 offset:1024
	ds_read_b128 v[208:211], v153 offset:2048
	ds_read_b128 v[212:215], v153 offset:3072
	global_load_lds_dwordx4 v130, s[28:29]
	s_add_i32 m0, s20, 0x2000
	s_nop 0
	global_load_lds_dwordx4 v134, s[28:29]
	s_waitcnt vmcnt(10)
	s_barrier
	s_waitcnt lgkmcnt(0)
	s_waitcnt lgkmcnt(0)
	v_mfma_f32_16x16x32_bf16 v[116:119], v[200:203], v[168:171], 0
	v_mfma_f32_16x16x32_bf16 v[112:115], v[208:211], v[168:171], 0
	v_mfma_f32_16x16x32_bf16 v[100:103], v[200:203], v[176:179], 0
	v_mfma_f32_16x16x32_bf16 v[96:99], v[208:211], v[176:179], 0
	v_mfma_f32_16x16x32_bf16 v[84:87], v[200:203], v[184:187], 0
	v_mfma_f32_16x16x32_bf16 v[80:83], v[208:211], v[184:187], 0
	v_mfma_f32_16x16x32_bf16 v[68:71], v[200:203], v[192:195], 0
	v_mfma_f32_16x16x32_bf16 v[64:67], v[208:211], v[192:195], 0
	v_mfma_f32_16x16x32_bf16 v[116:119], v[204:207], v[172:175], v[116:119]
	v_mfma_f32_16x16x32_bf16 v[112:115], v[212:215], v[172:175], v[112:115]
	v_mfma_f32_16x16x32_bf16 v[100:103], v[204:207], v[180:183], v[100:103]
	v_mfma_f32_16x16x32_bf16 v[96:99], v[212:215], v[180:183], v[96:99]
	v_mfma_f32_16x16x32_bf16 v[84:87], v[204:207], v[188:191], v[84:87]
	v_mfma_f32_16x16x32_bf16 v[80:83], v[212:215], v[188:191], v[80:83]
	v_mfma_f32_16x16x32_bf16 v[68:71], v[204:207], v[196:199], v[68:71]
	v_mfma_f32_16x16x32_bf16 v[64:67], v[212:215], v[196:199], v[64:67]
	s_mov_b32 m0, s41
	s_add_u32 s82, s30, 0x80
	s_addc_u32 s83, s31, 0
	s_barrier
	ds_read_b128 v[168:171], v152 offset:16384
	ds_read_b128 v[172:175], v152 offset:17408
	ds_read_b128 v[176:179], v152 offset:18432
	ds_read_b128 v[180:183], v152 offset:19456
	ds_read_b128 v[184:187], v152 offset:20480
	ds_read_b128 v[188:191], v152 offset:21504
	ds_read_b128 v[192:195], v152 offset:22528
	ds_read_b128 v[196:199], v152 offset:23552
	global_load_lds_dwordx4 v128, s[30:31]
	s_mov_b32 m0, s42
	s_nop 0
	global_load_lds_dwordx4 v132, s[30:31]
	s_barrier
	s_waitcnt lgkmcnt(0)
	s_waitcnt lgkmcnt(0)
	v_mfma_f32_16x16x32_bf16 v[60:63], v[144:147], v[168:171], 0
	v_mfma_f32_16x16x32_bf16 v[56:59], v[160:163], v[168:171], 0
	v_mfma_f32_16x16x32_bf16 v[44:47], v[144:147], v[176:179], 0
	v_mfma_f32_16x16x32_bf16 v[40:43], v[160:163], v[176:179], 0
	v_mfma_f32_16x16x32_bf16 v[28:31], v[144:147], v[184:187], 0
	v_mfma_f32_16x16x32_bf16 v[24:27], v[160:163], v[184:187], 0
	v_mfma_f32_16x16x32_bf16 v[12:15], v[144:147], v[192:195], 0
	v_mfma_f32_16x16x32_bf16 v[8:11], v[160:163], v[192:195], 0
	v_mfma_f32_16x16x32_bf16 v[60:63], v[156:159], v[172:175], v[60:63]
	v_mfma_f32_16x16x32_bf16 v[56:59], v[164:167], v[172:175], v[56:59]
	v_mfma_f32_16x16x32_bf16 v[44:47], v[156:159], v[180:183], v[44:47]
	v_mfma_f32_16x16x32_bf16 v[40:43], v[164:167], v[180:183], v[40:43]
	v_mfma_f32_16x16x32_bf16 v[28:31], v[156:159], v[188:191], v[28:31]
	v_mfma_f32_16x16x32_bf16 v[24:27], v[164:167], v[188:191], v[24:27]
	v_mfma_f32_16x16x32_bf16 v[12:15], v[156:159], v[196:199], v[12:15]
	v_mfma_f32_16x16x32_bf16 v[8:11], v[164:167], v[196:199], v[8:11]
	s_barrier
	s_add_u32 s20, s28, 0xb0000
	s_addc_u32 s21, s29, 0
	s_add_i32 s60, s52, s40
	s_mov_b32 m0, s60
	s_nop 0
	global_load_lds_dwordx4 v130, s[20:21]
	s_add_i32 m0, s60, 0x2000
	s_nop 0
	global_load_lds_dwordx4 v134, s[20:21]
	s_waitcnt vmcnt(8)
	s_barrier
	v_mfma_f32_16x16x32_bf16 v[52:55], v[200:203], v[168:171], 0
	v_mfma_f32_16x16x32_bf16 v[48:51], v[208:211], v[168:171], 0
	v_mfma_f32_16x16x32_bf16 v[36:39], v[200:203], v[176:179], 0
	v_mfma_f32_16x16x32_bf16 v[32:35], v[208:211], v[176:179], 0
	v_mfma_f32_16x16x32_bf16 v[20:23], v[200:203], v[184:187], 0
	v_mfma_f32_16x16x32_bf16 v[16:19], v[208:211], v[184:187], 0
	v_mfma_f32_16x16x32_bf16 v[4:7], v[200:203], v[192:195], 0
	v_mfma_f32_16x16x32_bf16 v[0:3], v[208:211], v[192:195], 0
	v_mfma_f32_16x16x32_bf16 v[52:55], v[204:207], v[172:175], v[52:55]
	v_mfma_f32_16x16x32_bf16 v[48:51], v[212:215], v[172:175], v[48:51]
	v_mfma_f32_16x16x32_bf16 v[36:39], v[204:207], v[180:183], v[36:39]
	v_mfma_f32_16x16x32_bf16 v[32:35], v[212:215], v[180:183], v[32:35]
	v_mfma_f32_16x16x32_bf16 v[20:23], v[204:207], v[188:191], v[20:23]
	v_mfma_f32_16x16x32_bf16 v[16:19], v[212:215], v[188:191], v[16:19]
	v_mfma_f32_16x16x32_bf16 v[4:7], v[204:207], v[196:199], v[4:7]
	v_mfma_f32_16x16x32_bf16 v[0:3], v[212:215], v[196:199], v[0:3]
	s_add_i32 s60, 0, 0x18000
	v_add_u32_e32 v155, s60, v149
	s_barrier
	s_branch .Lg248_mid
.LBB0_248:
	ds_read_b128 v[144:147], v151
	ds_read_b128 v[156:159], v151 offset:1024
	ds_read_b128 v[160:163], v151 offset:2048
	ds_read_b128 v[164:167], v151 offset:3072
	s_add_u32 s26, s20, 0x100
	s_addc_u32 s27, s21, 0
	s_cmp_eq_u32 s59, 40
	s_cselect_b32 s31, s9, s27
	s_cselect_b32 s30, s8, s26
	s_cselect_b32 s29, s11, s58
	s_cselect_b32 s28, s10, s57
	s_add_i32 m0, s41, 0xc000
	ds_read_b128 v[168:171], v152
	ds_read_b128 v[172:175], v152 offset:1024
	ds_read_b128 v[176:179], v152 offset:2048
	ds_read_b128 v[180:183], v152 offset:3072
	ds_read_b128 v[184:187], v152 offset:4096
	ds_read_b128 v[188:191], v152 offset:5120
	ds_read_b128 v[192:195], v152 offset:6144
	ds_read_b128 v[196:199], v152 offset:7168
	global_load_lds_dwordx4 v136, s[20:21]
	s_add_i32 m0, s41, 0xe000
	s_nop 0
	global_load_lds_dwordx4 v138, s[20:21]
	s_waitcnt lgkmcnt(8)
	s_barrier
	s_waitcnt lgkmcnt(0)
	s_waitcnt lgkmcnt(0)
	v_mfma_f32_16x16x32_bf16 v[124:127], v[144:147], v[168:171], v[124:127]
	v_mfma_f32_16x16x32_bf16 v[120:123], v[160:163], v[168:171], v[120:123]
	v_mfma_f32_16x16x32_bf16 v[108:111], v[144:147], v[176:179], v[108:111]
	v_mfma_f32_16x16x32_bf16 v[104:107], v[160:163], v[176:179], v[104:107]
	v_mfma_f32_16x16x32_bf16 v[92:95], v[144:147], v[184:187], v[92:95]
	v_mfma_f32_16x16x32_bf16 v[88:91], v[160:163], v[184:187], v[88:91]
	v_mfma_f32_16x16x32_bf16 v[76:79], v[144:147], v[192:195], v[76:79]
	v_mfma_f32_16x16x32_bf16 v[72:75], v[160:163], v[192:195], v[72:75]
	v_mfma_f32_16x16x32_bf16 v[124:127], v[156:159], v[172:175], v[124:127]
	v_mfma_f32_16x16x32_bf16 v[120:123], v[164:167], v[172:175], v[120:123]
	v_mfma_f32_16x16x32_bf16 v[108:111], v[156:159], v[180:183], v[108:111]
	v_mfma_f32_16x16x32_bf16 v[104:107], v[164:167], v[180:183], v[104:107]
	v_mfma_f32_16x16x32_bf16 v[92:95], v[156:159], v[188:191], v[92:95]
	v_mfma_f32_16x16x32_bf16 v[88:91], v[164:167], v[188:191], v[88:91]
	v_mfma_f32_16x16x32_bf16 v[76:79], v[156:159], v[196:199], v[76:79]
	v_mfma_f32_16x16x32_bf16 v[72:75], v[164:167], v[196:199], v[72:75]
	s_barrier
	s_add_i32 s20, s51, s40
	s_add_u32 s80, s28, 0x80
	s_addc_u32 s81, s29, 0
	s_mov_b32 m0, s20
	ds_read_b128 v[200:203], v153
	ds_read_b128 v[204:207], v153 offset:1024
	ds_read_b128 v[208:211], v153 offset:2048
	ds_read_b128 v[212:215], v153 offset:3072
	global_load_lds_dwordx4 v130, s[28:29]
	s_add_i32 m0, s20, 0x2000
	s_nop 0
	global_load_lds_dwordx4 v134, s[28:29]
	s_waitcnt vmcnt(10)
	s_barrier
	s_waitcnt lgkmcnt(0)
	s_waitcnt lgkmcnt(0)
	v_mfma_f32_16x16x32_bf16 v[116:119], v[200:203], v[168:171], v[116:119]
	v_mfma_f32_16x16x32_bf16 v[112:115], v[208:211], v[168:171], v[112:115]
	v_mfma_f32_16x16x32_bf16 v[100:103], v[200:203], v[176:179], v[100:103]
	v_mfma_f32_16x16x32_bf16 v[96:99], v[208:211], v[176:179], v[96:99]
	v_mfma_f32_16x16x32_bf16 v[84:87], v[200:203], v[184:187], v[84:87]
	v_mfma_f32_16x16x32_bf16 v[80:83], v[208:211], v[184:187], v[80:83]
	v_mfma_f32_16x16x32_bf16 v[68:71], v[200:203], v[192:195], v[68:71]
	v_mfma_f32_16x16x32_bf16 v[64:67], v[208:211], v[192:195], v[64:67]
	v_mfma_f32_16x16x32_bf16 v[116:119], v[204:207], v[172:175], v[116:119]
	v_mfma_f32_16x16x32_bf16 v[112:115], v[212:215], v[172:175], v[112:115]
	v_mfma_f32_16x16x32_bf16 v[100:103], v[204:207], v[180:183], v[100:103]
	v_mfma_f32_16x16x32_bf16 v[96:99], v[212:215], v[180:183], v[96:99]
	v_mfma_f32_16x16x32_bf16 v[84:87], v[204:207], v[188:191], v[84:87]
	v_mfma_f32_16x16x32_bf16 v[80:83], v[212:215], v[188:191], v[80:83]
	v_mfma_f32_16x16x32_bf16 v[68:71], v[204:207], v[196:199], v[68:71]
	v_mfma_f32_16x16x32_bf16 v[64:67], v[212:215], v[196:199], v[64:67]
	s_mov_b32 m0, s41
	s_add_u32 s82, s30, 0x80
	s_addc_u32 s83, s31, 0
	s_barrier
	ds_read_b128 v[168:171], v152 offset:16384
	ds_read_b128 v[172:175], v152 offset:17408
	ds_read_b128 v[176:179], v152 offset:18432
	ds_read_b128 v[180:183], v152 offset:19456
	ds_read_b128 v[184:187], v152 offset:20480
	ds_read_b128 v[188:191], v152 offset:21504
	ds_read_b128 v[192:195], v152 offset:22528
	ds_read_b128 v[196:199], v152 offset:23552
	global_load_lds_dwordx4 v128, s[30:31]
	s_mov_b32 m0, s42
	s_nop 0
	global_load_lds_dwordx4 v132, s[30:31]
	s_barrier
	s_waitcnt lgkmcnt(0)
	s_waitcnt lgkmcnt(0)
	v_mfma_f32_16x16x32_bf16 v[60:63], v[144:147], v[168:171], v[60:63]
	v_mfma_f32_16x16x32_bf16 v[56:59], v[160:163], v[168:171], v[56:59]
	v_mfma_f32_16x16x32_bf16 v[44:47], v[144:147], v[176:179], v[44:47]
	v_mfma_f32_16x16x32_bf16 v[40:43], v[160:163], v[176:179], v[40:43]
	v_mfma_f32_16x16x32_bf16 v[28:31], v[144:147], v[184:187], v[28:31]
	v_mfma_f32_16x16x32_bf16 v[24:27], v[160:163], v[184:187], v[24:27]
	v_mfma_f32_16x16x32_bf16 v[12:15], v[144:147], v[192:195], v[12:15]
	v_mfma_f32_16x16x32_bf16 v[8:11], v[160:163], v[192:195], v[8:11]
	v_mfma_f32_16x16x32_bf16 v[60:63], v[156:159], v[172:175], v[60:63]
	v_mfma_f32_16x16x32_bf16 v[56:59], v[164:167], v[172:175], v[56:59]
	v_mfma_f32_16x16x32_bf16 v[44:47], v[156:159], v[180:183], v[44:47]
	v_mfma_f32_16x16x32_bf16 v[40:43], v[164:167], v[180:183], v[40:43]
	v_mfma_f32_16x16x32_bf16 v[28:31], v[156:159], v[188:191], v[28:31]
	v_mfma_f32_16x16x32_bf16 v[24:27], v[164:167], v[188:191], v[24:27]
	v_mfma_f32_16x16x32_bf16 v[12:15], v[156:159], v[196:199], v[12:15]
	v_mfma_f32_16x16x32_bf16 v[8:11], v[164:167], v[196:199], v[8:11]
	s_barrier
	s_add_u32 s20, s28, 0xb0000
	s_addc_u32 s21, s29, 0
	s_add_i32 s60, s52, s40
	s_mov_b32 m0, s60
	s_nop 0
	global_load_lds_dwordx4 v130, s[20:21]
	s_add_i32 m0, s60, 0x2000
	s_nop 0
	global_load_lds_dwordx4 v134, s[20:21]
	s_waitcnt vmcnt(8)
	s_barrier
	v_mfma_f32_16x16x32_bf16 v[52:55], v[200:203], v[168:171], v[52:55]
	v_mfma_f32_16x16x32_bf16 v[48:51], v[208:211], v[168:171], v[48:51]
	v_mfma_f32_16x16x32_bf16 v[36:39], v[200:203], v[176:179], v[36:39]
	v_mfma_f32_16x16x32_bf16 v[32:35], v[208:211], v[176:179], v[32:35]
	v_mfma_f32_16x16x32_bf16 v[20:23], v[200:203], v[184:187], v[20:23]
	v_mfma_f32_16x16x32_bf16 v[16:19], v[208:211], v[184:187], v[16:19]
	v_mfma_f32_16x16x32_bf16 v[4:7], v[200:203], v[192:195], v[4:7]
	v_mfma_f32_16x16x32_bf16 v[0:3], v[208:211], v[192:195], v[0:3]
	v_mfma_f32_16x16x32_bf16 v[52:55], v[204:207], v[172:175], v[52:55]
	v_mfma_f32_16x16x32_bf16 v[48:51], v[212:215], v[172:175], v[48:51]
	v_mfma_f32_16x16x32_bf16 v[36:39], v[204:207], v[180:183], v[36:39]
	v_mfma_f32_16x16x32_bf16 v[32:35], v[212:215], v[180:183], v[32:35]
	v_mfma_f32_16x16x32_bf16 v[20:23], v[204:207], v[188:191], v[20:23]
	v_mfma_f32_16x16x32_bf16 v[16:19], v[212:215], v[188:191], v[16:19]
	v_mfma_f32_16x16x32_bf16 v[4:7], v[204:207], v[196:199], v[4:7]
	v_mfma_f32_16x16x32_bf16 v[0:3], v[212:215], v[196:199], v[0:3]
	s_add_i32 s60, 0, 0x18000
	v_add_u32_e32 v155, s60, v149
	s_barrier
.Lg248_mid:
	ds_read_b128 v[144:147], v155
	ds_read_b128 v[156:159], v155 offset:1024
	ds_read_b128 v[160:163], v155 offset:2048
	ds_read_b128 v[164:167], v155 offset:3072
	s_add_u32 s20, s30, 0xb0000
	s_addc_u32 s21, s31, 0
	s_mov_b32 m0, s43
	ds_read_b128 v[168:171], v152 offset:32768
	ds_read_b128 v[172:175], v152 offset:33792
	ds_read_b128 v[176:179], v152 offset:34816
	ds_read_b128 v[180:183], v152 offset:35840
	ds_read_b128 v[184:187], v152 offset:36864
	ds_read_b128 v[188:191], v152 offset:37888
	ds_read_b128 v[192:195], v152 offset:38912
	ds_read_b128 v[196:199], v152 offset:39936
	global_load_lds_dwordx4 v128, s[20:21]
	s_mov_b32 m0, s44
	s_nop 0
	global_load_lds_dwordx4 v132, s[20:21]
	s_waitcnt lgkmcnt(8)
	s_barrier
	s_waitcnt lgkmcnt(0)
	s_waitcnt lgkmcnt(0)
	v_mfma_f32_16x16x32_bf16 v[124:127], v[144:147], v[168:171], v[124:127]
	v_mfma_f32_16x16x32_bf16 v[120:123], v[160:163], v[168:171], v[120:123]
	v_mfma_f32_16x16x32_bf16 v[108:111], v[144:147], v[176:179], v[108:111]
	v_mfma_f32_16x16x32_bf16 v[104:107], v[160:163], v[176:179], v[104:107]
	v_mfma_f32_16x16x32_bf16 v[92:95], v[144:147], v[184:187], v[92:95]
	v_mfma_f32_16x16x32_bf16 v[88:91], v[160:163], v[184:187], v[88:91]
	v_mfma_f32_16x16x32_bf16 v[76:79], v[144:147], v[192:195], v[76:79]
	v_mfma_f32_16x16x32_bf16 v[72:75], v[160:163], v[192:195], v[72:75]
	v_mfma_f32_16x16x32_bf16 v[124:127], v[156:159], v[172:175], v[124:127]
	v_mfma_f32_16x16x32_bf16 v[120:123], v[164:167], v[172:175], v[120:123]
	v_mfma_f32_16x16x32_bf16 v[108:111], v[156:159], v[180:183], v[108:111]
	v_mfma_f32_16x16x32_bf16 v[104:107], v[164:167], v[180:183], v[104:107]
	v_mfma_f32_16x16x32_bf16 v[92:95], v[156:159], v[188:191], v[92:95]
	v_mfma_f32_16x16x32_bf16 v[88:91], v[164:167], v[188:191], v[88:91]
	v_mfma_f32_16x16x32_bf16 v[76:79], v[156:159], v[196:199], v[76:79]
	v_mfma_f32_16x16x32_bf16 v[72:75], v[164:167], v[196:199], v[72:75]
	s_barrier
	s_add_i32 s30, 0, 0x1c000
	s_add_i32 s20, s60, s40
	v_add_u32_e32 v155, s30, v149
	s_mov_b32 m0, s20
	ds_read_b128 v[200:203], v155
	ds_read_b128 v[204:207], v155 offset:1024
	ds_read_b128 v[208:211], v155 offset:2048
	ds_read_b128 v[212:215], v155 offset:3072
	global_load_lds_dwordx4 v130, s[80:81]
	s_add_i32 m0, s20, 0x2000
	s_nop 0
	global_load_lds_dwordx4 v134, s[80:81]
	s_waitcnt vmcnt(10)
	s_barrier
	s_waitcnt lgkmcnt(0)
	s_waitcnt lgkmcnt(0)
	v_mfma_f32_16x16x32_bf16 v[116:119], v[200:203], v[168:171], v[116:119]
	v_mfma_f32_16x16x32_bf16 v[112:115], v[208:211], v[168:171], v[112:115]
	v_mfma_f32_16x16x32_bf16 v[100:103], v[200:203], v[176:179], v[100:103]
	v_mfma_f32_16x16x32_bf16 v[96:99], v[208:211], v[176:179], v[96:99]
	v_mfma_f32_16x16x32_bf16 v[84:87], v[200:203], v[184:187], v[84:87]
	v_mfma_f32_16x16x32_bf16 v[80:83], v[208:211], v[184:187], v[80:83]
	v_mfma_f32_16x16x32_bf16 v[68:71], v[200:203], v[192:195], v[68:71]
	v_mfma_f32_16x16x32_bf16 v[64:67], v[208:211], v[192:195], v[64:67]
	v_mfma_f32_16x16x32_bf16 v[116:119], v[204:207], v[172:175], v[116:119]
	v_mfma_f32_16x16x32_bf16 v[112:115], v[212:215], v[172:175], v[112:115]
	v_mfma_f32_16x16x32_bf16 v[100:103], v[204:207], v[180:183], v[100:103]
	v_mfma_f32_16x16x32_bf16 v[96:99], v[212:215], v[180:183], v[96:99]
	v_mfma_f32_16x16x32_bf16 v[84:87], v[204:207], v[188:191], v[84:87]
	v_mfma_f32_16x16x32_bf16 v[80:83], v[212:215], v[188:191], v[80:83]
	v_mfma_f32_16x16x32_bf16 v[68:71], v[204:207], v[196:199], v[68:71]
	v_mfma_f32_16x16x32_bf16 v[64:67], v[212:215], v[196:199], v[64:67]
	s_mov_b32 m0, s46
	s_barrier
	ds_read_b128 v[168:171], v152 offset:49152
	ds_read_b128 v[172:175], v152 offset:50176
	ds_read_b128 v[176:179], v152 offset:51200
	ds_read_b128 v[180:183], v152 offset:52224
	ds_read_b128 v[184:187], v152 offset:53248
	ds_read_b128 v[188:191], v152 offset:54272
	ds_read_b128 v[192:195], v152 offset:55296
	ds_read_b128 v[196:199], v152 offset:56320
	global_load_lds_dwordx4 v128, s[82:83]
	s_mov_b32 m0, s47
	s_nop 0
	global_load_lds_dwordx4 v132, s[82:83]
	s_barrier
	s_waitcnt lgkmcnt(0)
	s_waitcnt lgkmcnt(0)
	v_mfma_f32_16x16x32_bf16 v[60:63], v[144:147], v[168:171], v[60:63]
	v_mfma_f32_16x16x32_bf16 v[56:59], v[160:163], v[168:171], v[56:59]
	v_mfma_f32_16x16x32_bf16 v[44:47], v[144:147], v[176:179], v[44:47]
	v_mfma_f32_16x16x32_bf16 v[40:43], v[160:163], v[176:179], v[40:43]
	v_mfma_f32_16x16x32_bf16 v[28:31], v[144:147], v[184:187], v[28:31]
	v_mfma_f32_16x16x32_bf16 v[24:27], v[160:163], v[184:187], v[24:27]
	v_mfma_f32_16x16x32_bf16 v[12:15], v[144:147], v[192:195], v[12:15]
	v_mfma_f32_16x16x32_bf16 v[8:11], v[160:163], v[192:195], v[8:11]
	v_mfma_f32_16x16x32_bf16 v[60:63], v[156:159], v[172:175], v[60:63]
	v_mfma_f32_16x16x32_bf16 v[56:59], v[164:167], v[172:175], v[56:59]
	v_mfma_f32_16x16x32_bf16 v[44:47], v[156:159], v[180:183], v[44:47]
	v_mfma_f32_16x16x32_bf16 v[40:43], v[164:167], v[180:183], v[40:43]
	v_mfma_f32_16x16x32_bf16 v[28:31], v[156:159], v[188:191], v[28:31]
	v_mfma_f32_16x16x32_bf16 v[24:27], v[164:167], v[188:191], v[24:27]
	v_mfma_f32_16x16x32_bf16 v[12:15], v[156:159], v[196:199], v[12:15]
	v_mfma_f32_16x16x32_bf16 v[8:11], v[164:167], v[196:199], v[8:11]
	s_barrier
	s_add_u32 s20, s28, 0xb0080
	s_addc_u32 s21, s29, 0
	s_add_i32 s28, s30, s40
	s_mov_b32 m0, s28
	s_nop 0
	global_load_lds_dwordx4 v130, s[20:21]
	s_add_i32 m0, s28, 0x2000
	s_nop 0
	global_load_lds_dwordx4 v134, s[20:21]
	s_waitcnt vmcnt(8)
	s_barrier
	v_mfma_f32_16x16x32_bf16 v[52:55], v[200:203], v[168:171], v[52:55]
	v_mfma_f32_16x16x32_bf16 v[48:51], v[208:211], v[168:171], v[48:51]
	v_mfma_f32_16x16x32_bf16 v[36:39], v[200:203], v[176:179], v[36:39]
	v_mfma_f32_16x16x32_bf16 v[32:35], v[208:211], v[176:179], v[32:35]
	v_mfma_f32_16x16x32_bf16 v[20:23], v[200:203], v[184:187], v[20:23]
	v_mfma_f32_16x16x32_bf16 v[16:19], v[208:211], v[184:187], v[16:19]
	v_mfma_f32_16x16x32_bf16 v[4:7], v[200:203], v[192:195], v[4:7]
	v_mfma_f32_16x16x32_bf16 v[0:3], v[208:211], v[192:195], v[0:3]
	v_mfma_f32_16x16x32_bf16 v[52:55], v[204:207], v[172:175], v[52:55]
	v_mfma_f32_16x16x32_bf16 v[48:51], v[212:215], v[172:175], v[48:51]
	v_mfma_f32_16x16x32_bf16 v[36:39], v[204:207], v[180:183], v[36:39]
	v_mfma_f32_16x16x32_bf16 v[32:35], v[212:215], v[180:183], v[32:35]
	v_mfma_f32_16x16x32_bf16 v[20:23], v[204:207], v[188:191], v[20:23]
	v_mfma_f32_16x16x32_bf16 v[16:19], v[212:215], v[188:191], v[16:19]
	v_mfma_f32_16x16x32_bf16 v[4:7], v[204:207], v[196:199], v[4:7]
	v_mfma_f32_16x16x32_bf16 v[0:3], v[212:215], v[196:199], v[0:3]
	s_add_i32 s59, s59, 2
	s_add_u32 s57, s57, 0x100
	s_addc_u32 s58, s58, 0
	s_cmp_gt_u32 s59, 41
	s_mov_b64 s[20:21], s[26:27]
	s_barrier
	s_cbranch_scc0 .LBB0_248
	s_setprio 0
	v_lshl_add_u32 v146, s56, 8, v148
	v_ashrrev_i32_e32 v147, 31, v146
	v_lshl_or_b32 v144, s12, 8, v150
	v_lshlrev_b64 v[156:157], 11, v[146:147]
	v_ashrrev_i32_e32 v145, 31, v144
	v_lshl_add_u64 v[156:157], s[14:15], 0, v[156:157]
	v_lshl_add_u64 v[166:167], v[144:145], 1, v[156:157]
	global_load_dwordx4 v[158:161], v[166:167], off
	global_load_dwordx4 v[162:165], v[166:167], off offset:256
	s_mov_b64 s[84:85], 0x8000
	s_mov_b64 s[86:87], 0x28000
	v_lshl_add_u64 v[232:233], v[166:167], 0, s[84:85]
	global_load_dwordx4 v[176:179], v[232:233], off
	global_load_dwordx4 v[180:183], v[232:233], off offset:256
	v_lshl_add_u64 v[232:233], v[232:233], 0, s[84:85]
	global_load_dwordx4 v[184:187], v[232:233], off
	global_load_dwordx4 v[188:191], v[232:233], off offset:256
	v_lshl_add_u64 v[232:233], v[232:233], 0, s[84:85]
	global_load_dwordx4 v[192:195], v[232:233], off
	global_load_dwordx4 v[196:199], v[232:233], off offset:256
	v_lshl_add_u64 v[232:233], v[232:233], 0, s[86:87]
	global_load_dwordx4 v[200:203], v[232:233], off
	global_load_dwordx4 v[204:207], v[232:233], off offset:256
	v_lshl_add_u64 v[232:233], v[232:233], 0, s[84:85]
	global_load_dwordx4 v[208:211], v[232:233], off
	global_load_dwordx4 v[212:215], v[232:233], off offset:256
	v_lshl_add_u64 v[232:233], v[232:233], 0, s[84:85]
	global_load_dwordx4 v[216:219], v[232:233], off
	global_load_dwordx4 v[220:223], v[232:233], off offset:256
	v_lshl_add_u64 v[232:233], v[232:233], 0, s[84:85]
	global_load_dwordx4 v[224:227], v[232:233], off
	global_load_dwordx4 v[228:231], v[232:233], off offset:256
	s_cmpk_gt_u32 s35, 0xff
	s_cbranch_scc1 .Lg248_nox
	s_barrier

.LBB0_358:
	s_ashr_i32 s21, s20, 31
	v_cmp_lt_i64_e32 vcc, s[30:31], v[162:163]
	s_lshl_b64 s[30:31], s[20:21], 19
	s_add_u32 s30, s47, s30
	s_addc_u32 s31, s48, s31
	s_and_b64 s[34:35], vcc, exec
	s_cselect_b32 s21, s31, s9
	s_cselect_b32 s71, s30, s8
	s_ashr_i32 s19, s18, 31
	s_lshl_b64 s[34:35], s[18:19], 19
	s_add_u32 s34, s49, s34
	s_addc_u32 s35, s50, s35
	s_and_b64 s[40:41], vcc, exec
	s_cselect_b32 s19, s35, s39
	s_cselect_b32 s72, s34, s38
	s_add_u32 s8, s8, 0x40080
	s_addc_u32 s9, s9, 0
	s_add_u32 s73, s38, 0x100
	s_addc_u32 s74, s39, 0
	s_mov_b32 s75, -2
	s_cmpk_lt_u32 s45, 0x100
	s_cbranch_scc1 .Lg359_noy
	s_setprio 1
	s_barrier
.Lg359_noy:
	ds_read_b128 v[128:131], v181
	ds_read_b128 v[132:135], v181 offset:1024
	ds_read_b128 v[136:139], v181 offset:2048
	ds_read_b128 v[166:169], v181 offset:3072
	s_add_u32 s38, s8, 0xfffc0080
	s_addc_u32 s39, s9, -1
	s_cmp_eq_u32 s75, 12
	s_cselect_b32 s41, s21, s39
	s_cselect_b32 s40, s71, s38
	s_cselect_b32 s39, s19, s74
	s_cselect_b32 s38, s72, s73
	s_add_i32 m0, s37, 0xc000
	ds_read_b128 v[170:173], v182
	ds_read_b128 v[174:177], v182 offset:1024
	ds_read_b128 v[192:195], v182 offset:2048
	ds_read_b128 v[196:199], v182 offset:3072
	ds_read_b128 v[200:203], v182 offset:4096
	ds_read_b128 v[204:207], v182 offset:5120
	ds_read_b128 v[208:211], v182 offset:6144
	ds_read_b128 v[212:215], v182 offset:7168
	global_load_lds_dwordx4 v158, s[8:9]
	s_add_i32 m0, s37, 0xe000
	s_nop 0
	global_load_lds_dwordx4 v160, s[8:9]
	s_waitcnt lgkmcnt(8)
	s_barrier
	s_waitcnt lgkmcnt(0)
	s_waitcnt lgkmcnt(0)
	v_mfma_f32_16x16x32_bf16 v[124:127], v[128:131], v[170:173], 0
	v_mfma_f32_16x16x32_bf16 v[116:119], v[136:139], v[170:173], 0
	v_mfma_f32_16x16x32_bf16 v[108:111], v[128:131], v[192:195], 0
	v_mfma_f32_16x16x32_bf16 v[100:103], v[136:139], v[192:195], 0
	v_mfma_f32_16x16x32_bf16 v[92:95], v[128:131], v[200:203], 0
	v_mfma_f32_16x16x32_bf16 v[84:87], v[136:139], v[200:203], 0
	v_mfma_f32_16x16x32_bf16 v[76:79], v[128:131], v[208:211], 0
	v_mfma_f32_16x16x32_bf16 v[68:71], v[136:139], v[208:211], 0
	v_mfma_f32_16x16x32_bf16 v[124:127], v[132:135], v[174:177], v[124:127]
	v_mfma_f32_16x16x32_bf16 v[116:119], v[166:169], v[174:177], v[116:119]
	v_mfma_f32_16x16x32_bf16 v[108:111], v[132:135], v[196:199], v[108:111]
	v_mfma_f32_16x16x32_bf16 v[100:103], v[166:169], v[196:199], v[100:103]
	v_mfma_f32_16x16x32_bf16 v[92:95], v[132:135], v[204:207], v[92:95]
	v_mfma_f32_16x16x32_bf16 v[84:87], v[166:169], v[204:207], v[84:87]
	v_mfma_f32_16x16x32_bf16 v[76:79], v[132:135], v[212:215], v[76:79]
	v_mfma_f32_16x16x32_bf16 v[68:71], v[166:169], v[212:215], v[68:71]
	s_barrier
	s_add_i32 s76, s63, s46
	s_add_u32 s80, s38, 0x80
	s_addc_u32 s81, s39, 0
	s_mov_b32 m0, s76
	ds_read_b128 v[216:219], v183
	ds_read_b128 v[220:223], v183 offset:1024
	ds_read_b128 v[224:227], v183 offset:2048
	ds_read_b128 v[228:231], v183 offset:3072
	global_load_lds_dwordx4 v144, s[38:39]
	s_add_i32 m0, s76, 0x2000
	s_nop 0
	global_load_lds_dwordx4 v148, s[38:39]
	s_waitcnt vmcnt(10)
	s_barrier
	s_waitcnt lgkmcnt(0)
	s_waitcnt lgkmcnt(0)
	v_mfma_f32_16x16x32_bf16 v[120:123], v[216:219], v[170:173], 0
	v_mfma_f32_16x16x32_bf16 v[112:115], v[224:227], v[170:173], 0
	v_mfma_f32_16x16x32_bf16 v[104:107], v[216:219], v[192:195], 0
	v_mfma_f32_16x16x32_bf16 v[96:99], v[224:227], v[192:195], 0
	v_mfma_f32_16x16x32_bf16 v[88:91], v[216:219], v[200:203], 0
	v_mfma_f32_16x16x32_bf16 v[80:83], v[224:227], v[200:203], 0
	v_mfma_f32_16x16x32_bf16 v[72:75], v[216:219], v[208:211], 0
	v_mfma_f32_16x16x32_bf16 v[64:67], v[224:227], v[208:211], 0
	v_mfma_f32_16x16x32_bf16 v[120:123], v[220:223], v[174:177], v[120:123]
	v_mfma_f32_16x16x32_bf16 v[112:115], v[228:231], v[174:177], v[112:115]
	v_mfma_f32_16x16x32_bf16 v[104:107], v[220:223], v[196:199], v[104:107]
	v_mfma_f32_16x16x32_bf16 v[96:99], v[228:231], v[196:199], v[96:99]
	v_mfma_f32_16x16x32_bf16 v[88:91], v[220:223], v[204:207], v[88:91]
	v_mfma_f32_16x16x32_bf16 v[80:83], v[228:231], v[204:207], v[80:83]
	v_mfma_f32_16x16x32_bf16 v[72:75], v[220:223], v[212:215], v[72:75]
	v_mfma_f32_16x16x32_bf16 v[64:67], v[228:231], v[212:215], v[64:67]
	s_mov_b32 m0, s37
	s_add_u32 s82, s40, 0x80
	s_addc_u32 s83, s41, 0
	s_barrier
	ds_read_b128 v[170:173], v182 offset:16384
	ds_read_b128 v[174:177], v182 offset:17408
	ds_read_b128 v[192:195], v182 offset:18432
	ds_read_b128 v[196:199], v182 offset:19456
	ds_read_b128 v[200:203], v182 offset:20480
	ds_read_b128 v[204:207], v182 offset:21504
	ds_read_b128 v[208:211], v182 offset:22528
	ds_read_b128 v[212:215], v182 offset:23552
	global_load_lds_dwordx4 v142, s[40:41]
	s_mov_b32 m0, s51
	s_nop 0
	global_load_lds_dwordx4 v146, s[40:41]
	s_barrier
	s_waitcnt lgkmcnt(0)
	s_waitcnt lgkmcnt(0)
	v_mfma_f32_16x16x32_bf16 v[60:63], v[128:131], v[170:173], 0
	v_mfma_f32_16x16x32_bf16 v[52:55], v[136:139], v[170:173], 0
	v_mfma_f32_16x16x32_bf16 v[44:47], v[128:131], v[192:195], 0
	v_mfma_f32_16x16x32_bf16 v[36:39], v[136:139], v[192:195], 0
	v_mfma_f32_16x16x32_bf16 v[28:31], v[128:131], v[200:203], 0
	v_mfma_f32_16x16x32_bf16 v[20:23], v[136:139], v[200:203], 0
	v_mfma_f32_16x16x32_bf16 v[12:15], v[128:131], v[208:211], 0
	v_mfma_f32_16x16x32_bf16 v[4:7], v[136:139], v[208:211], 0
	v_mfma_f32_16x16x32_bf16 v[60:63], v[132:135], v[174:177], v[60:63]
	v_mfma_f32_16x16x32_bf16 v[52:55], v[166:169], v[174:177], v[52:55]
	v_mfma_f32_16x16x32_bf16 v[44:47], v[132:135], v[196:199], v[44:47]
	v_mfma_f32_16x16x32_bf16 v[36:39], v[166:169], v[196:199], v[36:39]
	v_mfma_f32_16x16x32_bf16 v[28:31], v[132:135], v[204:207], v[28:31]
	v_mfma_f32_16x16x32_bf16 v[20:23], v[166:169], v[204:207], v[20:23]
	v_mfma_f32_16x16x32_bf16 v[12:15], v[132:135], v[212:215], v[12:15]
	v_mfma_f32_16x16x32_bf16 v[4:7], v[166:169], v[212:215], v[4:7]
	s_barrier
	s_add_u32 s76, s38, 0x40000
	s_addc_u32 s77, s39, 0
	s_add_i32 s78, s64, s46
	s_mov_b32 m0, s78
	s_nop 0
	global_load_lds_dwordx4 v144, s[76:77]
	s_add_i32 m0, s78, 0x2000
	s_nop 0
	global_load_lds_dwordx4 v148, s[76:77]
	s_waitcnt vmcnt(8)
	s_barrier
	v_mfma_f32_16x16x32_bf16 v[56:59], v[216:219], v[170:173], 0
	v_mfma_f32_16x16x32_bf16 v[48:51], v[224:227], v[170:173], 0
	v_mfma_f32_16x16x32_bf16 v[40:43], v[216:219], v[192:195], 0
	v_mfma_f32_16x16x32_bf16 v[32:35], v[224:227], v[192:195], 0
	v_mfma_f32_16x16x32_bf16 v[24:27], v[216:219], v[200:203], 0
	v_mfma_f32_16x16x32_bf16 v[16:19], v[224:227], v[200:203], 0
	v_mfma_f32_16x16x32_bf16 v[8:11], v[216:219], v[208:211], 0
	v_mfma_f32_16x16x32_bf16 v[0:3], v[224:227], v[208:211], 0
	v_mfma_f32_16x16x32_bf16 v[56:59], v[220:223], v[174:177], v[56:59]
	v_mfma_f32_16x16x32_bf16 v[48:51], v[228:231], v[174:177], v[48:51]
	v_mfma_f32_16x16x32_bf16 v[40:43], v[220:223], v[196:199], v[40:43]
	v_mfma_f32_16x16x32_bf16 v[32:35], v[228:231], v[196:199], v[32:35]
	v_mfma_f32_16x16x32_bf16 v[24:27], v[220:223], v[204:207], v[24:27]
	v_mfma_f32_16x16x32_bf16 v[16:19], v[228:231], v[204:207], v[16:19]
	v_mfma_f32_16x16x32_bf16 v[8:11], v[220:223], v[212:215], v[8:11]
	v_mfma_f32_16x16x32_bf16 v[0:3], v[228:231], v[212:215], v[0:3]
	s_add_i32 s76, 0, 0x18000
	v_add_u32_e32 v150, s76, v179
	s_barrier
	s_branch .Lg359_mid
.LBB0_359:
	ds_read_b128 v[128:131], v181
	ds_read_b128 v[132:135], v181 offset:1024
	ds_read_b128 v[136:139], v181 offset:2048
	ds_read_b128 v[166:169], v181 offset:3072
	s_add_u32 s38, s8, 0xfffc0080
	s_addc_u32 s39, s9, -1
	s_cmp_eq_u32 s75, 12
	s_cselect_b32 s41, s21, s39
	s_cselect_b32 s40, s71, s38
	s_cselect_b32 s39, s19, s74
	s_cselect_b32 s38, s72, s73
	s_add_i32 m0, s37, 0xc000
	ds_read_b128 v[170:173], v182
	ds_read_b128 v[174:177], v182 offset:1024
	ds_read_b128 v[192:195], v182 offset:2048
	ds_read_b128 v[196:199], v182 offset:3072
	ds_read_b128 v[200:203], v182 offset:4096
	ds_read_b128 v[204:207], v182 offset:5120
	ds_read_b128 v[208:211], v182 offset:6144
	ds_read_b128 v[212:215], v182 offset:7168
	global_load_lds_dwordx4 v158, s[8:9]
	s_add_i32 m0, s37, 0xe000
	s_nop 0
	global_load_lds_dwordx4 v160, s[8:9]
	s_waitcnt lgkmcnt(8)
	s_barrier
	s_waitcnt lgkmcnt(0)
	s_waitcnt lgkmcnt(0)
	v_mfma_f32_16x16x32_bf16 v[124:127], v[128:131], v[170:173], v[124:127]
	v_mfma_f32_16x16x32_bf16 v[116:119], v[136:139], v[170:173], v[116:119]
	v_mfma_f32_16x16x32_bf16 v[108:111], v[128:131], v[192:195], v[108:111]
	v_mfma_f32_16x16x32_bf16 v[100:103], v[136:139], v[192:195], v[100:103]
	v_mfma_f32_16x16x32_bf16 v[92:95], v[128:131], v[200:203], v[92:95]
	v_mfma_f32_16x16x32_bf16 v[84:87], v[136:139], v[200:203], v[84:87]
	v_mfma_f32_16x16x32_bf16 v[76:79], v[128:131], v[208:211], v[76:79]
	v_mfma_f32_16x16x32_bf16 v[68:71], v[136:139], v[208:211], v[68:71]
	v_mfma_f32_16x16x32_bf16 v[124:127], v[132:135], v[174:177], v[124:127]
	v_mfma_f32_16x16x32_bf16 v[116:119], v[166:169], v[174:177], v[116:119]
	v_mfma_f32_16x16x32_bf16 v[108:111], v[132:135], v[196:199], v[108:111]
	v_mfma_f32_16x16x32_bf16 v[100:103], v[166:169], v[196:199], v[100:103]
	v_mfma_f32_16x16x32_bf16 v[92:95], v[132:135], v[204:207], v[92:95]
	v_mfma_f32_16x16x32_bf16 v[84:87], v[166:169], v[204:207], v[84:87]
	v_mfma_f32_16x16x32_bf16 v[76:79], v[132:135], v[212:215], v[76:79]
	v_mfma_f32_16x16x32_bf16 v[68:71], v[166:169], v[212:215], v[68:71]
	s_barrier
	s_add_i32 s76, s63, s46
	s_add_u32 s80, s38, 0x80
	s_addc_u32 s81, s39, 0
	s_mov_b32 m0, s76
	ds_read_b128 v[216:219], v183
	ds_read_b128 v[220:223], v183 offset:1024
	ds_read_b128 v[224:227], v183 offset:2048
	ds_read_b128 v[228:231], v183 offset:3072
	global_load_lds_dwordx4 v144, s[38:39]
	s_add_i32 m0, s76, 0x2000
	s_nop 0
	global_load_lds_dwordx4 v148, s[38:39]
	s_waitcnt vmcnt(10)
	s_barrier
	s_waitcnt lgkmcnt(0)
	s_waitcnt lgkmcnt(0)
	v_mfma_f32_16x16x32_bf16 v[120:123], v[216:219], v[170:173], v[120:123]
	v_mfma_f32_16x16x32_bf16 v[112:115], v[224:227], v[170:173], v[112:115]
	v_mfma_f32_16x16x32_bf16 v[104:107], v[216:219], v[192:195], v[104:107]
	v_mfma_f32_16x16x32_bf16 v[96:99], v[224:227], v[192:195], v[96:99]
	v_mfma_f32_16x16x32_bf16 v[88:91], v[216:219], v[200:203], v[88:91]
	v_mfma_f32_16x16x32_bf16 v[80:83], v[224:227], v[200:203], v[80:83]
	v_mfma_f32_16x16x32_bf16 v[72:75], v[216:219], v[208:211], v[72:75]
	v_mfma_f32_16x16x32_bf16 v[64:67], v[224:227], v[208:211], v[64:67]
	v_mfma_f32_16x16x32_bf16 v[120:123], v[220:223], v[174:177], v[120:123]
	v_mfma_f32_16x16x32_bf16 v[112:115], v[228:231], v[174:177], v[112:115]
	v_mfma_f32_16x16x32_bf16 v[104:107], v[220:223], v[196:199], v[104:107]
	v_mfma_f32_16x16x32_bf16 v[96:99], v[228:231], v[196:199], v[96:99]
	v_mfma_f32_16x16x32_bf16 v[88:91], v[220:223], v[204:207], v[88:91]
	v_mfma_f32_16x16x32_bf16 v[80:83], v[228:231], v[204:207], v[80:83]
	v_mfma_f32_16x16x32_bf16 v[72:75], v[220:223], v[212:215], v[72:75]
	v_mfma_f32_16x16x32_bf16 v[64:67], v[228:231], v[212:215], v[64:67]
	s_mov_b32 m0, s37
	s_add_u32 s82, s40, 0x80
	s_addc_u32 s83, s41, 0
	s_barrier
	ds_read_b128 v[170:173], v182 offset:16384
	ds_read_b128 v[174:177], v182 offset:17408
	ds_read_b128 v[192:195], v182 offset:18432
	ds_read_b128 v[196:199], v182 offset:19456
	ds_read_b128 v[200:203], v182 offset:20480
	ds_read_b128 v[204:207], v182 offset:21504
	ds_read_b128 v[208:211], v182 offset:22528
	ds_read_b128 v[212:215], v182 offset:23552
	global_load_lds_dwordx4 v142, s[40:41]
	s_mov_b32 m0, s51
	s_nop 0
	global_load_lds_dwordx4 v146, s[40:41]
	s_barrier
	s_waitcnt lgkmcnt(0)
	s_waitcnt lgkmcnt(0)
	v_mfma_f32_16x16x32_bf16 v[60:63], v[128:131], v[170:173], v[60:63]
	v_mfma_f32_16x16x32_bf16 v[52:55], v[136:139], v[170:173], v[52:55]
	v_mfma_f32_16x16x32_bf16 v[44:47], v[128:131], v[192:195], v[44:47]
	v_mfma_f32_16x16x32_bf16 v[36:39], v[136:139], v[192:195], v[36:39]
	v_mfma_f32_16x16x32_bf16 v[28:31], v[128:131], v[200:203], v[28:31]
	v_mfma_f32_16x16x32_bf16 v[20:23], v[136:139], v[200:203], v[20:23]
	v_mfma_f32_16x16x32_bf16 v[12:15], v[128:131], v[208:211], v[12:15]
	v_mfma_f32_16x16x32_bf16 v[4:7], v[136:139], v[208:211], v[4:7]
	v_mfma_f32_16x16x32_bf16 v[60:63], v[132:135], v[174:177], v[60:63]
	v_mfma_f32_16x16x32_bf16 v[52:55], v[166:169], v[174:177], v[52:55]
	v_mfma_f32_16x16x32_bf16 v[44:47], v[132:135], v[196:199], v[44:47]
	v_mfma_f32_16x16x32_bf16 v[36:39], v[166:169], v[196:199], v[36:39]
	v_mfma_f32_16x16x32_bf16 v[28:31], v[132:135], v[204:207], v[28:31]
	v_mfma_f32_16x16x32_bf16 v[20:23], v[166:169], v[204:207], v[20:23]
	v_mfma_f32_16x16x32_bf16 v[12:15], v[132:135], v[212:215], v[12:15]
	v_mfma_f32_16x16x32_bf16 v[4:7], v[166:169], v[212:215], v[4:7]
	s_barrier
	s_add_u32 s76, s38, 0x40000
	s_addc_u32 s77, s39, 0
	s_add_i32 s78, s64, s46
	s_mov_b32 m0, s78
	s_nop 0
	global_load_lds_dwordx4 v144, s[76:77]
	s_add_i32 m0, s78, 0x2000
	s_nop 0
	global_load_lds_dwordx4 v148, s[76:77]
	s_waitcnt vmcnt(8)
	s_barrier
	v_mfma_f32_16x16x32_bf16 v[56:59], v[216:219], v[170:173], v[56:59]
	v_mfma_f32_16x16x32_bf16 v[48:51], v[224:227], v[170:173], v[48:51]
	v_mfma_f32_16x16x32_bf16 v[40:43], v[216:219], v[192:195], v[40:43]
	v_mfma_f32_16x16x32_bf16 v[32:35], v[224:227], v[192:195], v[32:35]
	v_mfma_f32_16x16x32_bf16 v[24:27], v[216:219], v[200:203], v[24:27]
	v_mfma_f32_16x16x32_bf16 v[16:19], v[224:227], v[200:203], v[16:19]
	v_mfma_f32_16x16x32_bf16 v[8:11], v[216:219], v[208:211], v[8:11]
	v_mfma_f32_16x16x32_bf16 v[0:3], v[224:227], v[208:211], v[0:3]
	v_mfma_f32_16x16x32_bf16 v[56:59], v[220:223], v[174:177], v[56:59]
	v_mfma_f32_16x16x32_bf16 v[48:51], v[228:231], v[174:177], v[48:51]
	v_mfma_f32_16x16x32_bf16 v[40:43], v[220:223], v[196:199], v[40:43]
	v_mfma_f32_16x16x32_bf16 v[32:35], v[228:231], v[196:199], v[32:35]
	v_mfma_f32_16x16x32_bf16 v[24:27], v[220:223], v[204:207], v[24:27]
	v_mfma_f32_16x16x32_bf16 v[16:19], v[228:231], v[204:207], v[16:19]
	v_mfma_f32_16x16x32_bf16 v[8:11], v[220:223], v[212:215], v[8:11]
	v_mfma_f32_16x16x32_bf16 v[0:3], v[228:231], v[212:215], v[0:3]
	s_add_i32 s76, 0, 0x18000
	v_add_u32_e32 v150, s76, v179
	s_barrier
.Lg359_mid:
	ds_read_b128 v[128:131], v150
	ds_read_b128 v[132:135], v150 offset:1024
	ds_read_b128 v[136:139], v150 offset:2048
	ds_read_b128 v[166:169], v150 offset:3072
	s_add_u32 s40, s40, 0x40000
	s_addc_u32 s41, s41, 0
	s_mov_b32 m0, s52
	ds_read_b128 v[170:173], v182 offset:32768
	ds_read_b128 v[174:177], v182 offset:33792
	ds_read_b128 v[192:195], v182 offset:34816
	ds_read_b128 v[196:199], v182 offset:35840
	ds_read_b128 v[200:203], v182 offset:36864
	ds_read_b128 v[204:207], v182 offset:37888
	ds_read_b128 v[208:211], v182 offset:38912
	ds_read_b128 v[212:215], v182 offset:39936
	global_load_lds_dwordx4 v142, s[40:41]
	s_mov_b32 m0, s53
	s_nop 0
	global_load_lds_dwordx4 v146, s[40:41]
	s_waitcnt lgkmcnt(8)
	s_barrier
	s_waitcnt lgkmcnt(0)
	s_waitcnt lgkmcnt(0)
	v_mfma_f32_16x16x32_bf16 v[124:127], v[128:131], v[170:173], v[124:127]
	v_mfma_f32_16x16x32_bf16 v[116:119], v[136:139], v[170:173], v[116:119]
	v_mfma_f32_16x16x32_bf16 v[108:111], v[128:131], v[192:195], v[108:111]
	v_mfma_f32_16x16x32_bf16 v[100:103], v[136:139], v[192:195], v[100:103]
	v_mfma_f32_16x16x32_bf16 v[92:95], v[128:131], v[200:203], v[92:95]
	v_mfma_f32_16x16x32_bf16 v[84:87], v[136:139], v[200:203], v[84:87]
	v_mfma_f32_16x16x32_bf16 v[76:79], v[128:131], v[208:211], v[76:79]
	v_mfma_f32_16x16x32_bf16 v[68:71], v[136:139], v[208:211], v[68:71]
	v_mfma_f32_16x16x32_bf16 v[124:127], v[132:135], v[174:177], v[124:127]
	v_mfma_f32_16x16x32_bf16 v[116:119], v[166:169], v[174:177], v[116:119]
	v_mfma_f32_16x16x32_bf16 v[108:111], v[132:135], v[196:199], v[108:111]
	v_mfma_f32_16x16x32_bf16 v[100:103], v[166:169], v[196:199], v[100:103]
	v_mfma_f32_16x16x32_bf16 v[92:95], v[132:135], v[204:207], v[92:95]
	v_mfma_f32_16x16x32_bf16 v[84:87], v[166:169], v[204:207], v[84:87]
	v_mfma_f32_16x16x32_bf16 v[76:79], v[132:135], v[212:215], v[76:79]
	v_mfma_f32_16x16x32_bf16 v[68:71], v[166:169], v[212:215], v[68:71]
	s_barrier
	s_add_i32 s40, 0, 0x1c000
	s_add_i32 s41, s76, s46
	v_add_u32_e32 v150, s40, v179
	s_mov_b32 m0, s41
	ds_read_b128 v[216:219], v150
	ds_read_b128 v[220:223], v150 offset:1024
	ds_read_b128 v[224:227], v150 offset:2048
	ds_read_b128 v[228:231], v150 offset:3072
	global_load_lds_dwordx4 v144, s[80:81]
	s_add_i32 m0, s41, 0x2000
	s_nop 0
	global_load_lds_dwordx4 v148, s[80:81]
	s_waitcnt vmcnt(10)
	s_barrier
	s_waitcnt lgkmcnt(0)
	s_waitcnt lgkmcnt(0)
	v_mfma_f32_16x16x32_bf16 v[120:123], v[216:219], v[170:173], v[120:123]
	v_mfma_f32_16x16x32_bf16 v[112:115], v[224:227], v[170:173], v[112:115]
	v_mfma_f32_16x16x32_bf16 v[104:107], v[216:219], v[192:195], v[104:107]
	v_mfma_f32_16x16x32_bf16 v[96:99], v[224:227], v[192:195], v[96:99]
	v_mfma_f32_16x16x32_bf16 v[88:91], v[216:219], v[200:203], v[88:91]
	v_mfma_f32_16x16x32_bf16 v[80:83], v[224:227], v[200:203], v[80:83]
	v_mfma_f32_16x16x32_bf16 v[72:75], v[216:219], v[208:211], v[72:75]
	v_mfma_f32_16x16x32_bf16 v[64:67], v[224:227], v[208:211], v[64:67]
	v_mfma_f32_16x16x32_bf16 v[120:123], v[220:223], v[174:177], v[120:123]
	v_mfma_f32_16x16x32_bf16 v[112:115], v[228:231], v[174:177], v[112:115]
	v_mfma_f32_16x16x32_bf16 v[104:107], v[220:223], v[196:199], v[104:107]
	v_mfma_f32_16x16x32_bf16 v[96:99], v[228:231], v[196:199], v[96:99]
	v_mfma_f32_16x16x32_bf16 v[88:91], v[220:223], v[204:207], v[88:91]
	v_mfma_f32_16x16x32_bf16 v[80:83], v[228:231], v[204:207], v[80:83]
	v_mfma_f32_16x16x32_bf16 v[72:75], v[220:223], v[212:215], v[72:75]
	v_mfma_f32_16x16x32_bf16 v[64:67], v[228:231], v[212:215], v[64:67]
	s_mov_b32 m0, s55
	s_barrier
	ds_read_b128 v[170:173], v182 offset:49152
	ds_read_b128 v[174:177], v182 offset:50176
	ds_read_b128 v[192:195], v182 offset:51200
	ds_read_b128 v[196:199], v182 offset:52224
	ds_read_b128 v[200:203], v182 offset:53248
	ds_read_b128 v[204:207], v182 offset:54272
	ds_read_b128 v[208:211], v182 offset:55296
	ds_read_b128 v[212:215], v182 offset:56320
	global_load_lds_dwordx4 v142, s[82:83]
	s_mov_b32 m0, s56
	s_nop 0
	global_load_lds_dwordx4 v146, s[82:83]
	s_barrier
	s_waitcnt lgkmcnt(0)
	s_waitcnt lgkmcnt(0)
	v_mfma_f32_16x16x32_bf16 v[60:63], v[128:131], v[170:173], v[60:63]
	v_mfma_f32_16x16x32_bf16 v[52:55], v[136:139], v[170:173], v[52:55]
	v_mfma_f32_16x16x32_bf16 v[44:47], v[128:131], v[192:195], v[44:47]
	v_mfma_f32_16x16x32_bf16 v[36:39], v[136:139], v[192:195], v[36:39]
	v_mfma_f32_16x16x32_bf16 v[28:31], v[128:131], v[200:203], v[28:31]
	v_mfma_f32_16x16x32_bf16 v[20:23], v[136:139], v[200:203], v[20:23]
	v_mfma_f32_16x16x32_bf16 v[12:15], v[128:131], v[208:211], v[12:15]
	v_mfma_f32_16x16x32_bf16 v[4:7], v[136:139], v[208:211], v[4:7]
	v_mfma_f32_16x16x32_bf16 v[60:63], v[132:135], v[174:177], v[60:63]
	v_mfma_f32_16x16x32_bf16 v[52:55], v[166:169], v[174:177], v[52:55]
	v_mfma_f32_16x16x32_bf16 v[44:47], v[132:135], v[196:199], v[44:47]
	v_mfma_f32_16x16x32_bf16 v[36:39], v[166:169], v[196:199], v[36:39]
	v_mfma_f32_16x16x32_bf16 v[28:31], v[132:135], v[204:207], v[28:31]
	v_mfma_f32_16x16x32_bf16 v[20:23], v[166:169], v[204:207], v[20:23]
	v_mfma_f32_16x16x32_bf16 v[12:15], v[132:135], v[212:215], v[12:15]
	v_mfma_f32_16x16x32_bf16 v[4:7], v[166:169], v[212:215], v[4:7]
	s_barrier
	s_add_u32 s38, s38, 0x40080
	s_addc_u32 s39, s39, 0
	s_add_i32 s40, s40, s46
	s_mov_b32 m0, s40
	s_nop 0
	global_load_lds_dwordx4 v144, s[38:39]
	s_add_i32 m0, s40, 0x2000
	s_nop 0
	global_load_lds_dwordx4 v148, s[38:39]
	s_waitcnt vmcnt(8)
	s_barrier
	v_mfma_f32_16x16x32_bf16 v[56:59], v[216:219], v[170:173], v[56:59]
	v_mfma_f32_16x16x32_bf16 v[48:51], v[224:227], v[170:173], v[48:51]
	v_mfma_f32_16x16x32_bf16 v[40:43], v[216:219], v[192:195], v[40:43]
	v_mfma_f32_16x16x32_bf16 v[32:35], v[224:227], v[192:195], v[32:35]
	v_mfma_f32_16x16x32_bf16 v[24:27], v[216:219], v[200:203], v[24:27]
	v_mfma_f32_16x16x32_bf16 v[16:19], v[224:227], v[200:203], v[16:19]
	v_mfma_f32_16x16x32_bf16 v[8:11], v[216:219], v[208:211], v[8:11]
	v_mfma_f32_16x16x32_bf16 v[0:3], v[224:227], v[208:211], v[0:3]
	v_mfma_f32_16x16x32_bf16 v[56:59], v[220:223], v[174:177], v[56:59]
	v_mfma_f32_16x16x32_bf16 v[48:51], v[228:231], v[174:177], v[48:51]
	v_mfma_f32_16x16x32_bf16 v[40:43], v[220:223], v[196:199], v[40:43]
	v_mfma_f32_16x16x32_bf16 v[32:35], v[228:231], v[196:199], v[32:35]
	v_mfma_f32_16x16x32_bf16 v[24:27], v[220:223], v[204:207], v[24:27]
	v_mfma_f32_16x16x32_bf16 v[16:19], v[228:231], v[204:207], v[16:19]
	v_mfma_f32_16x16x32_bf16 v[8:11], v[220:223], v[212:215], v[8:11]
	v_mfma_f32_16x16x32_bf16 v[0:3], v[228:231], v[212:215], v[0:3]
	s_add_i32 s75, s75, 2
	s_add_u32 s8, s8, 0x100
	s_addc_u32 s9, s9, 0
	s_add_u32 s73, s73, 0x100
	s_addc_u32 s74, s74, 0
	s_cmp_gt_u32 s75, 13
	s_barrier
	s_cbranch_scc0 .LBB0_359
	s_setprio 0
	s_cmpk_gt_u32 s45, 0xff
	s_cbranch_scc1 .Lg359_nox
	s_barrier

.LBB0_785:
	s_ashr_i32 s19, s18, 31
	v_cmp_lt_i64_e32 vcc, s[20:21], v[140:141]
	s_lshl_b64 s[20:21], s[18:19], 19
	s_add_u32 s20, s38, s20
	s_addc_u32 s21, s39, s21
	s_and_b64 s[26:27], vcc, exec
	s_cselect_b32 s19, s21, s29
	s_cselect_b32 s57, s20, s28
	s_ashr_i32 s17, s16, 31
	s_lshl_b64 s[26:27], s[16:17], 19
	s_add_u32 s26, s40, s26
	s_addc_u32 s27, s41, s27
	s_and_b64 s[34:35], vcc, exec
	s_cselect_b32 s17, s27, s31
	s_cselect_b32 s58, s26, s30
	s_add_u32 s28, s28, 0x40080
	s_addc_u32 s29, s29, 0
	s_add_u32 s59, s30, 0x100
	s_addc_u32 s60, s31, 0
	s_mov_b32 s61, -2
	s_waitcnt lgkmcnt(0)
	s_cmpk_lt_u32 s37, 0x100
	s_cbranch_scc1 .Lg786_noy
	s_setprio 1
	s_barrier
.Lg786_noy:
	ds_read_b128 v[144:147], v151
	ds_read_b128 v[156:159], v151 offset:1024
	ds_read_b128 v[160:163], v151 offset:2048
	ds_read_b128 v[164:167], v151 offset:3072
	s_add_u32 s30, s28, 0xfffc0080
	s_addc_u32 s31, s29, -1
	s_cmp_eq_u32 s61, 12
	s_cselect_b32 s35, s19, s31
	s_cselect_b32 s34, s57, s30
	s_cselect_b32 s31, s17, s60
	s_cselect_b32 s30, s58, s59
	s_add_i32 m0, s45, 0xc000
	ds_read_b128 v[168:171], v152
	ds_read_b128 v[172:175], v152 offset:1024
	ds_read_b128 v[176:179], v152 offset:2048
	ds_read_b128 v[180:183], v152 offset:3072
	ds_read_b128 v[184:187], v152 offset:4096
	ds_read_b128 v[188:191], v152 offset:5120
	ds_read_b128 v[192:195], v152 offset:6144
	ds_read_b128 v[196:199], v152 offset:7168
	global_load_lds_dwordx4 v136, s[28:29]
	s_add_i32 m0, s45, 0xe000
	s_nop 0
	global_load_lds_dwordx4 v138, s[28:29]
	s_waitcnt lgkmcnt(8)
	s_barrier
	s_waitcnt lgkmcnt(0)
	s_waitcnt lgkmcnt(0)
	v_mfma_f32_16x16x32_bf16 v[124:127], v[144:147], v[168:171], 0
	v_mfma_f32_16x16x32_bf16 v[120:123], v[160:163], v[168:171], 0
	v_mfma_f32_16x16x32_bf16 v[108:111], v[144:147], v[176:179], 0
	v_mfma_f32_16x16x32_bf16 v[104:107], v[160:163], v[176:179], 0
	v_mfma_f32_16x16x32_bf16 v[92:95], v[144:147], v[184:187], 0
	v_mfma_f32_16x16x32_bf16 v[88:91], v[160:163], v[184:187], 0
	v_mfma_f32_16x16x32_bf16 v[76:79], v[144:147], v[192:195], 0
	v_mfma_f32_16x16x32_bf16 v[72:75], v[160:163], v[192:195], 0
	v_mfma_f32_16x16x32_bf16 v[124:127], v[156:159], v[172:175], v[124:127]
	v_mfma_f32_16x16x32_bf16 v[120:123], v[164:167], v[172:175], v[120:123]
	v_mfma_f32_16x16x32_bf16 v[108:111], v[156:159], v[180:183], v[108:111]
	v_mfma_f32_16x16x32_bf16 v[104:107], v[164:167], v[180:183], v[104:107]
	v_mfma_f32_16x16x32_bf16 v[92:95], v[156:159], v[188:191], v[92:95]
	v_mfma_f32_16x16x32_bf16 v[88:91], v[164:167], v[188:191], v[88:91]
	v_mfma_f32_16x16x32_bf16 v[76:79], v[156:159], v[196:199], v[76:79]
	v_mfma_f32_16x16x32_bf16 v[72:75], v[164:167], v[196:199], v[72:75]
	s_barrier
	s_add_i32 s62, s53, s42
	s_add_u32 s80, s30, 0x80
	s_addc_u32 s81, s31, 0
	s_mov_b32 m0, s62
	ds_read_b128 v[200:203], v153
	ds_read_b128 v[204:207], v153 offset:1024
	ds_read_b128 v[208:211], v153 offset:2048
	ds_read_b128 v[212:215], v153 offset:3072
	global_load_lds_dwordx4 v132, s[30:31]
	s_add_i32 m0, s62, 0x2000
	s_nop 0
	global_load_lds_dwordx4 v128, s[30:31]
	s_waitcnt vmcnt(10)
	s_barrier
	s_waitcnt lgkmcnt(0)
	s_waitcnt lgkmcnt(0)
	v_mfma_f32_16x16x32_bf16 v[116:119], v[200:203], v[168:171], 0
	v_mfma_f32_16x16x32_bf16 v[112:115], v[208:211], v[168:171], 0
	v_mfma_f32_16x16x32_bf16 v[100:103], v[200:203], v[176:179], 0
	v_mfma_f32_16x16x32_bf16 v[96:99], v[208:211], v[176:179], 0
	v_mfma_f32_16x16x32_bf16 v[84:87], v[200:203], v[184:187], 0
	v_mfma_f32_16x16x32_bf16 v[80:83], v[208:211], v[184:187], 0
	v_mfma_f32_16x16x32_bf16 v[68:71], v[200:203], v[192:195], 0
	v_mfma_f32_16x16x32_bf16 v[64:67], v[208:211], v[192:195], 0
	v_mfma_f32_16x16x32_bf16 v[116:119], v[204:207], v[172:175], v[116:119]
	v_mfma_f32_16x16x32_bf16 v[112:115], v[212:215], v[172:175], v[112:115]
	v_mfma_f32_16x16x32_bf16 v[100:103], v[204:207], v[180:183], v[100:103]
	v_mfma_f32_16x16x32_bf16 v[96:99], v[212:215], v[180:183], v[96:99]
	v_mfma_f32_16x16x32_bf16 v[84:87], v[204:207], v[188:191], v[84:87]
	v_mfma_f32_16x16x32_bf16 v[80:83], v[212:215], v[188:191], v[80:83]
	v_mfma_f32_16x16x32_bf16 v[68:71], v[204:207], v[196:199], v[68:71]
	v_mfma_f32_16x16x32_bf16 v[64:67], v[212:215], v[196:199], v[64:67]
	s_mov_b32 m0, s45
	s_add_u32 s82, s34, 0x80
	s_addc_u32 s83, s35, 0
	s_barrier
	ds_read_b128 v[168:171], v152 offset:16384
	ds_read_b128 v[172:175], v152 offset:17408
	ds_read_b128 v[176:179], v152 offset:18432
	ds_read_b128 v[180:183], v152 offset:19456
	ds_read_b128 v[184:187], v152 offset:20480
	ds_read_b128 v[188:191], v152 offset:21504
	ds_read_b128 v[192:195], v152 offset:22528
	ds_read_b128 v[196:199], v152 offset:23552
	global_load_lds_dwordx4 v134, s[34:35]
	s_mov_b32 m0, s46
	s_nop 0
	global_load_lds_dwordx4 v130, s[34:35]
	s_barrier
	s_waitcnt lgkmcnt(0)
	s_waitcnt lgkmcnt(0)
	v_mfma_f32_16x16x32_bf16 v[60:63], v[144:147], v[168:171], 0
	v_mfma_f32_16x16x32_bf16 v[56:59], v[160:163], v[168:171], 0
	v_mfma_f32_16x16x32_bf16 v[44:47], v[144:147], v[176:179], 0
	v_mfma_f32_16x16x32_bf16 v[40:43], v[160:163], v[176:179], 0
	v_mfma_f32_16x16x32_bf16 v[28:31], v[144:147], v[184:187], 0
	v_mfma_f32_16x16x32_bf16 v[24:27], v[160:163], v[184:187], 0
	v_mfma_f32_16x16x32_bf16 v[12:15], v[144:147], v[192:195], 0
	v_mfma_f32_16x16x32_bf16 v[8:11], v[160:163], v[192:195], 0
	v_mfma_f32_16x16x32_bf16 v[60:63], v[156:159], v[172:175], v[60:63]
	v_mfma_f32_16x16x32_bf16 v[56:59], v[164:167], v[172:175], v[56:59]
	v_mfma_f32_16x16x32_bf16 v[44:47], v[156:159], v[180:183], v[44:47]
	v_mfma_f32_16x16x32_bf16 v[40:43], v[164:167], v[180:183], v[40:43]
	v_mfma_f32_16x16x32_bf16 v[28:31], v[156:159], v[188:191], v[28:31]
	v_mfma_f32_16x16x32_bf16 v[24:27], v[164:167], v[188:191], v[24:27]
	v_mfma_f32_16x16x32_bf16 v[12:15], v[156:159], v[196:199], v[12:15]
	v_mfma_f32_16x16x32_bf16 v[8:11], v[164:167], v[196:199], v[8:11]
	s_barrier
	s_add_u32 s62, s30, 0x40000
	s_addc_u32 s63, s31, 0
	s_add_i32 s64, s54, s42
	s_mov_b32 m0, s64
	s_nop 0
	global_load_lds_dwordx4 v132, s[62:63]
	s_add_i32 m0, s64, 0x2000
	s_nop 0
	global_load_lds_dwordx4 v128, s[62:63]
	s_waitcnt vmcnt(8)
	s_barrier
	v_mfma_f32_16x16x32_bf16 v[52:55], v[200:203], v[168:171], 0
	v_mfma_f32_16x16x32_bf16 v[48:51], v[208:211], v[168:171], 0
	v_mfma_f32_16x16x32_bf16 v[36:39], v[200:203], v[176:179], 0
	v_mfma_f32_16x16x32_bf16 v[32:35], v[208:211], v[176:179], 0
	v_mfma_f32_16x16x32_bf16 v[20:23], v[200:203], v[184:187], 0
	v_mfma_f32_16x16x32_bf16 v[16:19], v[208:211], v[184:187], 0
	v_mfma_f32_16x16x32_bf16 v[4:7], v[200:203], v[192:195], 0
	v_mfma_f32_16x16x32_bf16 v[0:3], v[208:211], v[192:195], 0
	v_mfma_f32_16x16x32_bf16 v[52:55], v[204:207], v[172:175], v[52:55]
	v_mfma_f32_16x16x32_bf16 v[48:51], v[212:215], v[172:175], v[48:51]
	v_mfma_f32_16x16x32_bf16 v[36:39], v[204:207], v[180:183], v[36:39]
	v_mfma_f32_16x16x32_bf16 v[32:35], v[212:215], v[180:183], v[32:35]
	v_mfma_f32_16x16x32_bf16 v[20:23], v[204:207], v[188:191], v[20:23]
	v_mfma_f32_16x16x32_bf16 v[16:19], v[212:215], v[188:191], v[16:19]
	v_mfma_f32_16x16x32_bf16 v[4:7], v[204:207], v[196:199], v[4:7]
	v_mfma_f32_16x16x32_bf16 v[0:3], v[212:215], v[196:199], v[0:3]
	s_add_i32 s62, 0, 0x18000
	v_add_u32_e32 v155, s62, v149
	s_barrier
	s_branch .Lg786_mid
.LBB0_786:
	ds_read_b128 v[144:147], v151
	ds_read_b128 v[156:159], v151 offset:1024
	ds_read_b128 v[160:163], v151 offset:2048
	ds_read_b128 v[164:167], v151 offset:3072
	s_add_u32 s30, s28, 0xfffc0080
	s_addc_u32 s31, s29, -1
	s_cmp_eq_u32 s61, 12
	s_cselect_b32 s35, s19, s31
	s_cselect_b32 s34, s57, s30
	s_cselect_b32 s31, s17, s60
	s_cselect_b32 s30, s58, s59
	s_add_i32 m0, s45, 0xc000
	ds_read_b128 v[168:171], v152
	ds_read_b128 v[172:175], v152 offset:1024
	ds_read_b128 v[176:179], v152 offset:2048
	ds_read_b128 v[180:183], v152 offset:3072
	ds_read_b128 v[184:187], v152 offset:4096
	ds_read_b128 v[188:191], v152 offset:5120
	ds_read_b128 v[192:195], v152 offset:6144
	ds_read_b128 v[196:199], v152 offset:7168
	global_load_lds_dwordx4 v136, s[28:29]
	s_add_i32 m0, s45, 0xe000
	s_nop 0
	global_load_lds_dwordx4 v138, s[28:29]
	s_waitcnt lgkmcnt(8)
	s_barrier
	s_waitcnt lgkmcnt(0)
	s_waitcnt lgkmcnt(0)
	v_mfma_f32_16x16x32_bf16 v[124:127], v[144:147], v[168:171], v[124:127]
	v_mfma_f32_16x16x32_bf16 v[120:123], v[160:163], v[168:171], v[120:123]
	v_mfma_f32_16x16x32_bf16 v[108:111], v[144:147], v[176:179], v[108:111]
	v_mfma_f32_16x16x32_bf16 v[104:107], v[160:163], v[176:179], v[104:107]
	v_mfma_f32_16x16x32_bf16 v[92:95], v[144:147], v[184:187], v[92:95]
	v_mfma_f32_16x16x32_bf16 v[88:91], v[160:163], v[184:187], v[88:91]
	v_mfma_f32_16x16x32_bf16 v[76:79], v[144:147], v[192:195], v[76:79]
	v_mfma_f32_16x16x32_bf16 v[72:75], v[160:163], v[192:195], v[72:75]
	v_mfma_f32_16x16x32_bf16 v[124:127], v[156:159], v[172:175], v[124:127]
	v_mfma_f32_16x16x32_bf16 v[120:123], v[164:167], v[172:175], v[120:123]
	v_mfma_f32_16x16x32_bf16 v[108:111], v[156:159], v[180:183], v[108:111]
	v_mfma_f32_16x16x32_bf16 v[104:107], v[164:167], v[180:183], v[104:107]
	v_mfma_f32_16x16x32_bf16 v[92:95], v[156:159], v[188:191], v[92:95]
	v_mfma_f32_16x16x32_bf16 v[88:91], v[164:167], v[188:191], v[88:91]
	v_mfma_f32_16x16x32_bf16 v[76:79], v[156:159], v[196:199], v[76:79]
	v_mfma_f32_16x16x32_bf16 v[72:75], v[164:167], v[196:199], v[72:75]
	s_barrier
	s_add_i32 s62, s53, s42
	s_add_u32 s80, s30, 0x80
	s_addc_u32 s81, s31, 0
	s_mov_b32 m0, s62
	ds_read_b128 v[200:203], v153
	ds_read_b128 v[204:207], v153 offset:1024
	ds_read_b128 v[208:211], v153 offset:2048
	ds_read_b128 v[212:215], v153 offset:3072
	global_load_lds_dwordx4 v132, s[30:31]
	s_add_i32 m0, s62, 0x2000
	s_nop 0
	global_load_lds_dwordx4 v128, s[30:31]
	s_waitcnt vmcnt(10)
	s_barrier
	s_waitcnt lgkmcnt(0)
	s_waitcnt lgkmcnt(0)
	v_mfma_f32_16x16x32_bf16 v[116:119], v[200:203], v[168:171], v[116:119]
	v_mfma_f32_16x16x32_bf16 v[112:115], v[208:211], v[168:171], v[112:115]
	v_mfma_f32_16x16x32_bf16 v[100:103], v[200:203], v[176:179], v[100:103]
	v_mfma_f32_16x16x32_bf16 v[96:99], v[208:211], v[176:179], v[96:99]
	v_mfma_f32_16x16x32_bf16 v[84:87], v[200:203], v[184:187], v[84:87]
	v_mfma_f32_16x16x32_bf16 v[80:83], v[208:211], v[184:187], v[80:83]
	v_mfma_f32_16x16x32_bf16 v[68:71], v[200:203], v[192:195], v[68:71]
	v_mfma_f32_16x16x32_bf16 v[64:67], v[208:211], v[192:195], v[64:67]
	v_mfma_f32_16x16x32_bf16 v[116:119], v[204:207], v[172:175], v[116:119]
	v_mfma_f32_16x16x32_bf16 v[112:115], v[212:215], v[172:175], v[112:115]
	v_mfma_f32_16x16x32_bf16 v[100:103], v[204:207], v[180:183], v[100:103]
	v_mfma_f32_16x16x32_bf16 v[96:99], v[212:215], v[180:183], v[96:99]
	v_mfma_f32_16x16x32_bf16 v[84:87], v[204:207], v[188:191], v[84:87]
	v_mfma_f32_16x16x32_bf16 v[80:83], v[212:215], v[188:191], v[80:83]
	v_mfma_f32_16x16x32_bf16 v[68:71], v[204:207], v[196:199], v[68:71]
	v_mfma_f32_16x16x32_bf16 v[64:67], v[212:215], v[196:199], v[64:67]
	s_mov_b32 m0, s45
	s_add_u32 s82, s34, 0x80
	s_addc_u32 s83, s35, 0
	s_barrier
	ds_read_b128 v[168:171], v152 offset:16384
	ds_read_b128 v[172:175], v152 offset:17408
	ds_read_b128 v[176:179], v152 offset:18432
	ds_read_b128 v[180:183], v152 offset:19456
	ds_read_b128 v[184:187], v152 offset:20480
	ds_read_b128 v[188:191], v152 offset:21504
	ds_read_b128 v[192:195], v152 offset:22528
	ds_read_b128 v[196:199], v152 offset:23552
	global_load_lds_dwordx4 v134, s[34:35]
	s_mov_b32 m0, s46
	s_nop 0
	global_load_lds_dwordx4 v130, s[34:35]
	s_barrier
	s_waitcnt lgkmcnt(0)
	s_waitcnt lgkmcnt(0)
	v_mfma_f32_16x16x32_bf16 v[60:63], v[144:147], v[168:171], v[60:63]
	v_mfma_f32_16x16x32_bf16 v[56:59], v[160:163], v[168:171], v[56:59]
	v_mfma_f32_16x16x32_bf16 v[44:47], v[144:147], v[176:179], v[44:47]
	v_mfma_f32_16x16x32_bf16 v[40:43], v[160:163], v[176:179], v[40:43]
	v_mfma_f32_16x16x32_bf16 v[28:31], v[144:147], v[184:187], v[28:31]
	v_mfma_f32_16x16x32_bf16 v[24:27], v[160:163], v[184:187], v[24:27]
	v_mfma_f32_16x16x32_bf16 v[12:15], v[144:147], v[192:195], v[12:15]
	v_mfma_f32_16x16x32_bf16 v[8:11], v[160:163], v[192:195], v[8:11]
	v_mfma_f32_16x16x32_bf16 v[60:63], v[156:159], v[172:175], v[60:63]
	v_mfma_f32_16x16x32_bf16 v[56:59], v[164:167], v[172:175], v[56:59]
	v_mfma_f32_16x16x32_bf16 v[44:47], v[156:159], v[180:183], v[44:47]
	v_mfma_f32_16x16x32_bf16 v[40:43], v[164:167], v[180:183], v[40:43]
	v_mfma_f32_16x16x32_bf16 v[28:31], v[156:159], v[188:191], v[28:31]
	v_mfma_f32_16x16x32_bf16 v[24:27], v[164:167], v[188:191], v[24:27]
	v_mfma_f32_16x16x32_bf16 v[12:15], v[156:159], v[196:199], v[12:15]
	v_mfma_f32_16x16x32_bf16 v[8:11], v[164:167], v[196:199], v[8:11]
	s_barrier
	s_add_u32 s62, s30, 0x40000
	s_addc_u32 s63, s31, 0
	s_add_i32 s64, s54, s42
	s_mov_b32 m0, s64
	s_nop 0
	global_load_lds_dwordx4 v132, s[62:63]
	s_add_i32 m0, s64, 0x2000
	s_nop 0
	global_load_lds_dwordx4 v128, s[62:63]
	s_waitcnt vmcnt(8)
	s_barrier
	v_mfma_f32_16x16x32_bf16 v[52:55], v[200:203], v[168:171], v[52:55]
	v_mfma_f32_16x16x32_bf16 v[48:51], v[208:211], v[168:171], v[48:51]
	v_mfma_f32_16x16x32_bf16 v[36:39], v[200:203], v[176:179], v[36:39]
	v_mfma_f32_16x16x32_bf16 v[32:35], v[208:211], v[176:179], v[32:35]
	v_mfma_f32_16x16x32_bf16 v[20:23], v[200:203], v[184:187], v[20:23]
	v_mfma_f32_16x16x32_bf16 v[16:19], v[208:211], v[184:187], v[16:19]
	v_mfma_f32_16x16x32_bf16 v[4:7], v[200:203], v[192:195], v[4:7]
	v_mfma_f32_16x16x32_bf16 v[0:3], v[208:211], v[192:195], v[0:3]
	v_mfma_f32_16x16x32_bf16 v[52:55], v[204:207], v[172:175], v[52:55]
	v_mfma_f32_16x16x32_bf16 v[48:51], v[212:215], v[172:175], v[48:51]
	v_mfma_f32_16x16x32_bf16 v[36:39], v[204:207], v[180:183], v[36:39]
	v_mfma_f32_16x16x32_bf16 v[32:35], v[212:215], v[180:183], v[32:35]
	v_mfma_f32_16x16x32_bf16 v[20:23], v[204:207], v[188:191], v[20:23]
	v_mfma_f32_16x16x32_bf16 v[16:19], v[212:215], v[188:191], v[16:19]
	v_mfma_f32_16x16x32_bf16 v[4:7], v[204:207], v[196:199], v[4:7]
	v_mfma_f32_16x16x32_bf16 v[0:3], v[212:215], v[196:199], v[0:3]
	s_add_i32 s62, 0, 0x18000
	v_add_u32_e32 v155, s62, v149
	s_barrier
.Lg786_mid:
	ds_read_b128 v[144:147], v155
	ds_read_b128 v[156:159], v155 offset:1024
	ds_read_b128 v[160:163], v155 offset:2048
	ds_read_b128 v[164:167], v155 offset:3072
	s_add_u32 s34, s34, 0x40000
	s_addc_u32 s35, s35, 0
	s_mov_b32 m0, s47
	ds_read_b128 v[168:171], v152 offset:32768
	ds_read_b128 v[172:175], v152 offset:33792
	ds_read_b128 v[176:179], v152 offset:34816
	ds_read_b128 v[180:183], v152 offset:35840
	ds_read_b128 v[184:187], v152 offset:36864
	ds_read_b128 v[188:191], v152 offset:37888
	ds_read_b128 v[192:195], v152 offset:38912
	ds_read_b128 v[196:199], v152 offset:39936
	global_load_lds_dwordx4 v134, s[34:35]
	s_mov_b32 m0, s48
	s_nop 0
	global_load_lds_dwordx4 v130, s[34:35]
	s_waitcnt lgkmcnt(8)
	s_barrier
	s_waitcnt lgkmcnt(0)
	s_waitcnt lgkmcnt(0)
	v_mfma_f32_16x16x32_bf16 v[124:127], v[144:147], v[168:171], v[124:127]
	v_mfma_f32_16x16x32_bf16 v[120:123], v[160:163], v[168:171], v[120:123]
	v_mfma_f32_16x16x32_bf16 v[108:111], v[144:147], v[176:179], v[108:111]
	v_mfma_f32_16x16x32_bf16 v[104:107], v[160:163], v[176:179], v[104:107]
	v_mfma_f32_16x16x32_bf16 v[92:95], v[144:147], v[184:187], v[92:95]
	v_mfma_f32_16x16x32_bf16 v[88:91], v[160:163], v[184:187], v[88:91]
	v_mfma_f32_16x16x32_bf16 v[76:79], v[144:147], v[192:195], v[76:79]
	v_mfma_f32_16x16x32_bf16 v[72:75], v[160:163], v[192:195], v[72:75]
	v_mfma_f32_16x16x32_bf16 v[124:127], v[156:159], v[172:175], v[124:127]
	v_mfma_f32_16x16x32_bf16 v[120:123], v[164:167], v[172:175], v[120:123]
	v_mfma_f32_16x16x32_bf16 v[108:111], v[156:159], v[180:183], v[108:111]
	v_mfma_f32_16x16x32_bf16 v[104:107], v[164:167], v[180:183], v[104:107]
	v_mfma_f32_16x16x32_bf16 v[92:95], v[156:159], v[188:191], v[92:95]
	v_mfma_f32_16x16x32_bf16 v[88:91], v[164:167], v[188:191], v[88:91]
	v_mfma_f32_16x16x32_bf16 v[76:79], v[156:159], v[196:199], v[76:79]
	v_mfma_f32_16x16x32_bf16 v[72:75], v[164:167], v[196:199], v[72:75]
	s_barrier
	s_add_i32 s34, 0, 0x1c000
	s_add_i32 s35, s62, s42
	v_add_u32_e32 v155, s34, v149
	s_mov_b32 m0, s35
	ds_read_b128 v[200:203], v155
	ds_read_b128 v[204:207], v155 offset:1024
	ds_read_b128 v[208:211], v155 offset:2048
	ds_read_b128 v[212:215], v155 offset:3072
	global_load_lds_dwordx4 v132, s[80:81]
	s_add_i32 m0, s35, 0x2000
	s_nop 0
	global_load_lds_dwordx4 v128, s[80:81]
	s_waitcnt vmcnt(10)
	s_barrier
	s_waitcnt lgkmcnt(0)
	s_waitcnt lgkmcnt(0)
	v_mfma_f32_16x16x32_bf16 v[116:119], v[200:203], v[168:171], v[116:119]
	v_mfma_f32_16x16x32_bf16 v[112:115], v[208:211], v[168:171], v[112:115]
	v_mfma_f32_16x16x32_bf16 v[100:103], v[200:203], v[176:179], v[100:103]
	v_mfma_f32_16x16x32_bf16 v[96:99], v[208:211], v[176:179], v[96:99]
	v_mfma_f32_16x16x32_bf16 v[84:87], v[200:203], v[184:187], v[84:87]
	v_mfma_f32_16x16x32_bf16 v[80:83], v[208:211], v[184:187], v[80:83]
	v_mfma_f32_16x16x32_bf16 v[68:71], v[200:203], v[192:195], v[68:71]
	v_mfma_f32_16x16x32_bf16 v[64:67], v[208:211], v[192:195], v[64:67]
	v_mfma_f32_16x16x32_bf16 v[116:119], v[204:207], v[172:175], v[116:119]
	v_mfma_f32_16x16x32_bf16 v[112:115], v[212:215], v[172:175], v[112:115]
	v_mfma_f32_16x16x32_bf16 v[100:103], v[204:207], v[180:183], v[100:103]
	v_mfma_f32_16x16x32_bf16 v[96:99], v[212:215], v[180:183], v[96:99]
	v_mfma_f32_16x16x32_bf16 v[84:87], v[204:207], v[188:191], v[84:87]
	v_mfma_f32_16x16x32_bf16 v[80:83], v[212:215], v[188:191], v[80:83]
	v_mfma_f32_16x16x32_bf16 v[68:71], v[204:207], v[196:199], v[68:71]
	v_mfma_f32_16x16x32_bf16 v[64:67], v[212:215], v[196:199], v[64:67]
	s_mov_b32 m0, s50
	s_barrier
	ds_read_b128 v[168:171], v152 offset:49152
	ds_read_b128 v[172:175], v152 offset:50176
	ds_read_b128 v[176:179], v152 offset:51200
	ds_read_b128 v[180:183], v152 offset:52224
	ds_read_b128 v[184:187], v152 offset:53248
	ds_read_b128 v[188:191], v152 offset:54272
	ds_read_b128 v[192:195], v152 offset:55296
	ds_read_b128 v[196:199], v152 offset:56320
	global_load_lds_dwordx4 v134, s[82:83]
	s_mov_b32 m0, s51
	s_nop 0
	global_load_lds_dwordx4 v130, s[82:83]
	s_barrier
	s_waitcnt lgkmcnt(0)
	s_waitcnt lgkmcnt(0)
	v_mfma_f32_16x16x32_bf16 v[60:63], v[144:147], v[168:171], v[60:63]
	v_mfma_f32_16x16x32_bf16 v[56:59], v[160:163], v[168:171], v[56:59]
	v_mfma_f32_16x16x32_bf16 v[44:47], v[144:147], v[176:179], v[44:47]
	v_mfma_f32_16x16x32_bf16 v[40:43], v[160:163], v[176:179], v[40:43]
	v_mfma_f32_16x16x32_bf16 v[28:31], v[144:147], v[184:187], v[28:31]
	v_mfma_f32_16x16x32_bf16 v[24:27], v[160:163], v[184:187], v[24:27]
	v_mfma_f32_16x16x32_bf16 v[12:15], v[144:147], v[192:195], v[12:15]
	v_mfma_f32_16x16x32_bf16 v[8:11], v[160:163], v[192:195], v[8:11]
	v_mfma_f32_16x16x32_bf16 v[60:63], v[156:159], v[172:175], v[60:63]
	v_mfma_f32_16x16x32_bf16 v[56:59], v[164:167], v[172:175], v[56:59]
	v_mfma_f32_16x16x32_bf16 v[44:47], v[156:159], v[180:183], v[44:47]
	v_mfma_f32_16x16x32_bf16 v[40:43], v[164:167], v[180:183], v[40:43]
	v_mfma_f32_16x16x32_bf16 v[28:31], v[156:159], v[188:191], v[28:31]
	v_mfma_f32_16x16x32_bf16 v[24:27], v[164:167], v[188:191], v[24:27]
	v_mfma_f32_16x16x32_bf16 v[12:15], v[156:159], v[196:199], v[12:15]
	v_mfma_f32_16x16x32_bf16 v[8:11], v[164:167], v[196:199], v[8:11]
	s_barrier
	s_add_u32 s30, s30, 0x40080
	s_addc_u32 s31, s31, 0
	s_add_i32 s34, s34, s42
	s_mov_b32 m0, s34
	s_nop 0
	global_load_lds_dwordx4 v132, s[30:31]
	s_add_i32 m0, s34, 0x2000
	s_nop 0
	global_load_lds_dwordx4 v128, s[30:31]
	s_waitcnt vmcnt(8)
	s_barrier
	v_mfma_f32_16x16x32_bf16 v[52:55], v[200:203], v[168:171], v[52:55]
	v_mfma_f32_16x16x32_bf16 v[48:51], v[208:211], v[168:171], v[48:51]
	v_mfma_f32_16x16x32_bf16 v[36:39], v[200:203], v[176:179], v[36:39]
	v_mfma_f32_16x16x32_bf16 v[32:35], v[208:211], v[176:179], v[32:35]
	v_mfma_f32_16x16x32_bf16 v[20:23], v[200:203], v[184:187], v[20:23]
	v_mfma_f32_16x16x32_bf16 v[16:19], v[208:211], v[184:187], v[16:19]
	v_mfma_f32_16x16x32_bf16 v[4:7], v[200:203], v[192:195], v[4:7]
	v_mfma_f32_16x16x32_bf16 v[0:3], v[208:211], v[192:195], v[0:3]
	v_mfma_f32_16x16x32_bf16 v[52:55], v[204:207], v[172:175], v[52:55]
	v_mfma_f32_16x16x32_bf16 v[48:51], v[212:215], v[172:175], v[48:51]
	v_mfma_f32_16x16x32_bf16 v[36:39], v[204:207], v[180:183], v[36:39]
	v_mfma_f32_16x16x32_bf16 v[32:35], v[212:215], v[180:183], v[32:35]
	v_mfma_f32_16x16x32_bf16 v[20:23], v[204:207], v[188:191], v[20:23]
	v_mfma_f32_16x16x32_bf16 v[16:19], v[212:215], v[188:191], v[16:19]
	v_mfma_f32_16x16x32_bf16 v[4:7], v[204:207], v[196:199], v[4:7]
	v_mfma_f32_16x16x32_bf16 v[0:3], v[212:215], v[196:199], v[0:3]
	s_add_i32 s61, s61, 2
	s_add_u32 s28, s28, 0x100
	s_addc_u32 s29, s29, 0
	s_add_u32 s59, s59, 0x100
	s_addc_u32 s60, s60, 0
	s_cmp_gt_u32 s61, 13
	s_barrier
	s_cbranch_scc0 .LBB0_786
	s_setprio 0
	v_lshl_add_u32 v146, s8, 8, v148
	v_ashrrev_i32_e32 v147, 31, v146
	v_lshl_or_b32 v144, s56, 8, v150
	v_lshlrev_b64 v[156:157], 11, v[146:147]
	v_ashrrev_i32_e32 v145, 31, v144
	v_lshl_add_u64 v[156:157], s[10:11], 0, v[156:157]
	v_lshl_add_u64 v[166:167], v[144:145], 1, v[156:157]
	global_load_dwordx4 v[158:161], v[166:167], off
	global_load_dwordx4 v[162:165], v[166:167], off offset:256
	s_mov_b64 s[84:85], 0x8000
	s_mov_b64 s[86:87], 0x28000
	v_lshl_add_u64 v[232:233], v[166:167], 0, s[84:85]
	global_load_dwordx4 v[176:179], v[232:233], off
	global_load_dwordx4 v[180:183], v[232:233], off offset:256
	v_lshl_add_u64 v[232:233], v[232:233], 0, s[84:85]
	global_load_dwordx4 v[184:187], v[232:233], off
	global_load_dwordx4 v[188:191], v[232:233], off offset:256
	v_lshl_add_u64 v[232:233], v[232:233], 0, s[84:85]
	global_load_dwordx4 v[192:195], v[232:233], off
	global_load_dwordx4 v[196:199], v[232:233], off offset:256
	v_lshl_add_u64 v[232:233], v[232:233], 0, s[86:87]
	global_load_dwordx4 v[200:203], v[232:233], off
	global_load_dwordx4 v[204:207], v[232:233], off offset:256
	v_lshl_add_u64 v[232:233], v[232:233], 0, s[84:85]
	global_load_dwordx4 v[208:211], v[232:233], off
	global_load_dwordx4 v[212:215], v[232:233], off offset:256
	v_lshl_add_u64 v[232:233], v[232:233], 0, s[84:85]
	global_load_dwordx4 v[216:219], v[232:233], off
	global_load_dwordx4 v[220:223], v[232:233], off offset:256
	v_lshl_add_u64 v[232:233], v[232:233], 0, s[84:85]
	global_load_dwordx4 v[224:227], v[232:233], off
	global_load_dwordx4 v[228:231], v[232:233], off offset:256
	s_cmpk_gt_u32 s37, 0xff
	s_cbranch_scc1 .Lg786_nox
	s_barrier

.LBB0_892:
	s_ashr_i32 s13, s12, 31
	v_cmp_lt_i64_e32 vcc, s[14:15], v[140:141]
	s_lshl_b64 s[14:15], s[12:13], 19
	s_add_u32 s14, s37, s14
	s_addc_u32 s15, s38, s15
	s_and_b64 s[16:17], vcc, exec
	s_cselect_b32 s13, s15, s21
	s_cselect_b32 s53, s14, s20
	s_ashr_i32 s11, s10, 31
	s_lshl_b64 s[16:17], s[10:11], 19
	s_add_u32 s16, s39, s16
	s_addc_u32 s17, s40, s17
	s_and_b64 s[28:29], vcc, exec
	s_cselect_b32 s11, s17, s27
	s_cselect_b32 s54, s16, s26
	s_add_u32 s20, s20, 0x40080
	s_addc_u32 s21, s21, 0
	s_add_u32 s55, s26, 0x100
	s_addc_u32 s56, s27, 0
	s_mov_b32 s57, -2
	s_cmpk_lt_u32 s30, 0x100
	s_cbranch_scc1 .Lg893_noy
	s_setprio 1
	s_barrier
.Lg893_noy:
	ds_read_b128 v[152:155], v148
	ds_read_b128 v[156:159], v148 offset:1024
	ds_read_b128 v[160:163], v148 offset:2048
	ds_read_b128 v[164:167], v148 offset:3072
	s_add_u32 s26, s20, 0xfffc0080
	s_addc_u32 s27, s21, -1
	s_cmp_eq_u32 s57, 12
	s_cselect_b32 s29, s13, s27
	s_cselect_b32 s28, s53, s26
	s_cselect_b32 s27, s11, s56
	s_cselect_b32 s26, s54, s55
	s_add_i32 m0, s19, 0xc000
	ds_read_b128 v[168:171], v149
	ds_read_b128 v[172:175], v149 offset:1024
	ds_read_b128 v[176:179], v149 offset:2048
	ds_read_b128 v[180:183], v149 offset:3072
	ds_read_b128 v[184:187], v149 offset:4096
	ds_read_b128 v[188:191], v149 offset:5120
	ds_read_b128 v[192:195], v149 offset:6144
	ds_read_b128 v[196:199], v149 offset:7168
	global_load_lds_dwordx4 v136, s[20:21]
	s_add_i32 m0, s19, 0xe000
	s_nop 0
	global_load_lds_dwordx4 v138, s[20:21]
	s_waitcnt lgkmcnt(8)
	s_barrier
	s_waitcnt lgkmcnt(0)
	s_waitcnt lgkmcnt(0)
	v_mfma_f32_16x16x32_bf16 v[124:127], v[152:155], v[168:171], 0
	v_mfma_f32_16x16x32_bf16 v[120:123], v[160:163], v[168:171], 0
	v_mfma_f32_16x16x32_bf16 v[108:111], v[152:155], v[176:179], 0
	v_mfma_f32_16x16x32_bf16 v[104:107], v[160:163], v[176:179], 0
	v_mfma_f32_16x16x32_bf16 v[92:95], v[152:155], v[184:187], 0
	v_mfma_f32_16x16x32_bf16 v[88:91], v[160:163], v[184:187], 0
	v_mfma_f32_16x16x32_bf16 v[76:79], v[152:155], v[192:195], 0
	v_mfma_f32_16x16x32_bf16 v[72:75], v[160:163], v[192:195], 0
	v_mfma_f32_16x16x32_bf16 v[124:127], v[156:159], v[172:175], v[124:127]
	v_mfma_f32_16x16x32_bf16 v[120:123], v[164:167], v[172:175], v[120:123]
	v_mfma_f32_16x16x32_bf16 v[108:111], v[156:159], v[180:183], v[108:111]
	v_mfma_f32_16x16x32_bf16 v[104:107], v[164:167], v[180:183], v[104:107]
	v_mfma_f32_16x16x32_bf16 v[92:95], v[156:159], v[188:191], v[92:95]
	v_mfma_f32_16x16x32_bf16 v[88:91], v[164:167], v[188:191], v[88:91]
	v_mfma_f32_16x16x32_bf16 v[76:79], v[156:159], v[196:199], v[76:79]
	v_mfma_f32_16x16x32_bf16 v[72:75], v[164:167], v[196:199], v[72:75]
	s_barrier
	s_add_i32 s58, s47, s31
	s_add_u32 s80, s26, 0x80
	s_addc_u32 s81, s27, 0
	s_mov_b32 m0, s58
	ds_read_b128 v[200:203], v150
	ds_read_b128 v[204:207], v150 offset:1024
	ds_read_b128 v[208:211], v150 offset:2048
	ds_read_b128 v[212:215], v150 offset:3072
	global_load_lds_dwordx4 v132, s[26:27]
	s_add_i32 m0, s58, 0x2000
	s_nop 0
	global_load_lds_dwordx4 v128, s[26:27]
	s_waitcnt vmcnt(10)
	s_barrier
	s_waitcnt lgkmcnt(0)
	s_waitcnt lgkmcnt(0)
	v_mfma_f32_16x16x32_bf16 v[116:119], v[200:203], v[168:171], 0
	v_mfma_f32_16x16x32_bf16 v[112:115], v[208:211], v[168:171], 0
	v_mfma_f32_16x16x32_bf16 v[100:103], v[200:203], v[176:179], 0
	v_mfma_f32_16x16x32_bf16 v[96:99], v[208:211], v[176:179], 0
	v_mfma_f32_16x16x32_bf16 v[84:87], v[200:203], v[184:187], 0
	v_mfma_f32_16x16x32_bf16 v[80:83], v[208:211], v[184:187], 0
	v_mfma_f32_16x16x32_bf16 v[68:71], v[200:203], v[192:195], 0
	v_mfma_f32_16x16x32_bf16 v[64:67], v[208:211], v[192:195], 0
	v_mfma_f32_16x16x32_bf16 v[116:119], v[204:207], v[172:175], v[116:119]
	v_mfma_f32_16x16x32_bf16 v[112:115], v[212:215], v[172:175], v[112:115]
	v_mfma_f32_16x16x32_bf16 v[100:103], v[204:207], v[180:183], v[100:103]
	v_mfma_f32_16x16x32_bf16 v[96:99], v[212:215], v[180:183], v[96:99]
	v_mfma_f32_16x16x32_bf16 v[84:87], v[204:207], v[188:191], v[84:87]
	v_mfma_f32_16x16x32_bf16 v[80:83], v[212:215], v[188:191], v[80:83]
	v_mfma_f32_16x16x32_bf16 v[68:71], v[204:207], v[196:199], v[68:71]
	v_mfma_f32_16x16x32_bf16 v[64:67], v[212:215], v[196:199], v[64:67]
	s_mov_b32 m0, s19
	s_add_u32 s82, s28, 0x80
	s_addc_u32 s83, s29, 0
	s_barrier
	ds_read_b128 v[168:171], v149 offset:16384
	ds_read_b128 v[172:175], v149 offset:17408
	ds_read_b128 v[176:179], v149 offset:18432
	ds_read_b128 v[180:183], v149 offset:19456
	ds_read_b128 v[184:187], v149 offset:20480
	ds_read_b128 v[188:191], v149 offset:21504
	ds_read_b128 v[192:195], v149 offset:22528
	ds_read_b128 v[196:199], v149 offset:23552
	global_load_lds_dwordx4 v134, s[28:29]
	s_mov_b32 m0, s42
	s_nop 0
	global_load_lds_dwordx4 v130, s[28:29]
	s_barrier
	s_waitcnt lgkmcnt(0)
	s_waitcnt lgkmcnt(0)
	v_mfma_f32_16x16x32_bf16 v[60:63], v[152:155], v[168:171], 0
	v_mfma_f32_16x16x32_bf16 v[56:59], v[160:163], v[168:171], 0
	v_mfma_f32_16x16x32_bf16 v[44:47], v[152:155], v[176:179], 0
	v_mfma_f32_16x16x32_bf16 v[40:43], v[160:163], v[176:179], 0
	v_mfma_f32_16x16x32_bf16 v[28:31], v[152:155], v[184:187], 0
	v_mfma_f32_16x16x32_bf16 v[24:27], v[160:163], v[184:187], 0
	v_mfma_f32_16x16x32_bf16 v[12:15], v[152:155], v[192:195], 0
	v_mfma_f32_16x16x32_bf16 v[8:11], v[160:163], v[192:195], 0
	v_mfma_f32_16x16x32_bf16 v[60:63], v[156:159], v[172:175], v[60:63]
	v_mfma_f32_16x16x32_bf16 v[56:59], v[164:167], v[172:175], v[56:59]
	v_mfma_f32_16x16x32_bf16 v[44:47], v[156:159], v[180:183], v[44:47]
	v_mfma_f32_16x16x32_bf16 v[40:43], v[164:167], v[180:183], v[40:43]
	v_mfma_f32_16x16x32_bf16 v[28:31], v[156:159], v[188:191], v[28:31]
	v_mfma_f32_16x16x32_bf16 v[24:27], v[164:167], v[188:191], v[24:27]
	v_mfma_f32_16x16x32_bf16 v[12:15], v[156:159], v[196:199], v[12:15]
	v_mfma_f32_16x16x32_bf16 v[8:11], v[164:167], v[196:199], v[8:11]
	s_barrier
	s_add_u32 s58, s26, 0x40000
	s_addc_u32 s59, s27, 0
	s_add_i32 s60, s48, s31
	s_mov_b32 m0, s60
	s_nop 0
	global_load_lds_dwordx4 v132, s[58:59]
	s_add_i32 m0, s60, 0x2000
	s_nop 0
	global_load_lds_dwordx4 v128, s[58:59]
	s_waitcnt vmcnt(8)
	s_barrier
	v_mfma_f32_16x16x32_bf16 v[52:55], v[200:203], v[168:171], 0
	v_mfma_f32_16x16x32_bf16 v[48:51], v[208:211], v[168:171], 0
	v_mfma_f32_16x16x32_bf16 v[36:39], v[200:203], v[176:179], 0
	v_mfma_f32_16x16x32_bf16 v[32:35], v[208:211], v[176:179], 0
	v_mfma_f32_16x16x32_bf16 v[20:23], v[200:203], v[184:187], 0
	v_mfma_f32_16x16x32_bf16 v[16:19], v[208:211], v[184:187], 0
	v_mfma_f32_16x16x32_bf16 v[4:7], v[200:203], v[192:195], 0
	v_mfma_f32_16x16x32_bf16 v[0:3], v[208:211], v[192:195], 0
	v_mfma_f32_16x16x32_bf16 v[52:55], v[204:207], v[172:175], v[52:55]
	v_mfma_f32_16x16x32_bf16 v[48:51], v[212:215], v[172:175], v[48:51]
	v_mfma_f32_16x16x32_bf16 v[36:39], v[204:207], v[180:183], v[36:39]
	v_mfma_f32_16x16x32_bf16 v[32:35], v[212:215], v[180:183], v[32:35]
	v_mfma_f32_16x16x32_bf16 v[20:23], v[204:207], v[188:191], v[20:23]
	v_mfma_f32_16x16x32_bf16 v[16:19], v[212:215], v[188:191], v[16:19]
	v_mfma_f32_16x16x32_bf16 v[4:7], v[204:207], v[196:199], v[4:7]
	v_mfma_f32_16x16x32_bf16 v[0:3], v[212:215], v[196:199], v[0:3]
	s_add_i32 s58, 0, 0x18000
	v_add_u32_e32 v151, s58, v145
	s_barrier
	s_branch .Lg893_mid
.LBB0_893:
	ds_read_b128 v[152:155], v148
	ds_read_b128 v[156:159], v148 offset:1024
	ds_read_b128 v[160:163], v148 offset:2048
	ds_read_b128 v[164:167], v148 offset:3072
	s_add_u32 s26, s20, 0xfffc0080
	s_addc_u32 s27, s21, -1
	s_cmp_eq_u32 s57, 12
	s_cselect_b32 s29, s13, s27
	s_cselect_b32 s28, s53, s26
	s_cselect_b32 s27, s11, s56
	s_cselect_b32 s26, s54, s55
	s_add_i32 m0, s19, 0xc000
	ds_read_b128 v[168:171], v149
	ds_read_b128 v[172:175], v149 offset:1024
	ds_read_b128 v[176:179], v149 offset:2048
	ds_read_b128 v[180:183], v149 offset:3072
	ds_read_b128 v[184:187], v149 offset:4096
	ds_read_b128 v[188:191], v149 offset:5120
	ds_read_b128 v[192:195], v149 offset:6144
	ds_read_b128 v[196:199], v149 offset:7168
	global_load_lds_dwordx4 v136, s[20:21]
	s_add_i32 m0, s19, 0xe000
	s_nop 0
	global_load_lds_dwordx4 v138, s[20:21]
	s_waitcnt lgkmcnt(8)
	s_barrier
	s_waitcnt lgkmcnt(0)
	s_waitcnt lgkmcnt(0)
	v_mfma_f32_16x16x32_bf16 v[124:127], v[152:155], v[168:171], v[124:127]
	v_mfma_f32_16x16x32_bf16 v[120:123], v[160:163], v[168:171], v[120:123]
	v_mfma_f32_16x16x32_bf16 v[108:111], v[152:155], v[176:179], v[108:111]
	v_mfma_f32_16x16x32_bf16 v[104:107], v[160:163], v[176:179], v[104:107]
	v_mfma_f32_16x16x32_bf16 v[92:95], v[152:155], v[184:187], v[92:95]
	v_mfma_f32_16x16x32_bf16 v[88:91], v[160:163], v[184:187], v[88:91]
	v_mfma_f32_16x16x32_bf16 v[76:79], v[152:155], v[192:195], v[76:79]
	v_mfma_f32_16x16x32_bf16 v[72:75], v[160:163], v[192:195], v[72:75]
	v_mfma_f32_16x16x32_bf16 v[124:127], v[156:159], v[172:175], v[124:127]
	v_mfma_f32_16x16x32_bf16 v[120:123], v[164:167], v[172:175], v[120:123]
	v_mfma_f32_16x16x32_bf16 v[108:111], v[156:159], v[180:183], v[108:111]
	v_mfma_f32_16x16x32_bf16 v[104:107], v[164:167], v[180:183], v[104:107]
	v_mfma_f32_16x16x32_bf16 v[92:95], v[156:159], v[188:191], v[92:95]
	v_mfma_f32_16x16x32_bf16 v[88:91], v[164:167], v[188:191], v[88:91]
	v_mfma_f32_16x16x32_bf16 v[76:79], v[156:159], v[196:199], v[76:79]
	v_mfma_f32_16x16x32_bf16 v[72:75], v[164:167], v[196:199], v[72:75]
	s_barrier
	s_add_i32 s58, s47, s31
	s_add_u32 s80, s26, 0x80
	s_addc_u32 s81, s27, 0
	s_mov_b32 m0, s58
	ds_read_b128 v[200:203], v150
	ds_read_b128 v[204:207], v150 offset:1024
	ds_read_b128 v[208:211], v150 offset:2048
	ds_read_b128 v[212:215], v150 offset:3072
	global_load_lds_dwordx4 v132, s[26:27]
	s_add_i32 m0, s58, 0x2000
	s_nop 0
	global_load_lds_dwordx4 v128, s[26:27]
	s_waitcnt vmcnt(10)
	s_barrier
	s_waitcnt lgkmcnt(0)
	s_waitcnt lgkmcnt(0)
	v_mfma_f32_16x16x32_bf16 v[116:119], v[200:203], v[168:171], v[116:119]
	v_mfma_f32_16x16x32_bf16 v[112:115], v[208:211], v[168:171], v[112:115]
	v_mfma_f32_16x16x32_bf16 v[100:103], v[200:203], v[176:179], v[100:103]
	v_mfma_f32_16x16x32_bf16 v[96:99], v[208:211], v[176:179], v[96:99]
	v_mfma_f32_16x16x32_bf16 v[84:87], v[200:203], v[184:187], v[84:87]
	v_mfma_f32_16x16x32_bf16 v[80:83], v[208:211], v[184:187], v[80:83]
	v_mfma_f32_16x16x32_bf16 v[68:71], v[200:203], v[192:195], v[68:71]
	v_mfma_f32_16x16x32_bf16 v[64:67], v[208:211], v[192:195], v[64:67]
	v_mfma_f32_16x16x32_bf16 v[116:119], v[204:207], v[172:175], v[116:119]
	v_mfma_f32_16x16x32_bf16 v[112:115], v[212:215], v[172:175], v[112:115]
	v_mfma_f32_16x16x32_bf16 v[100:103], v[204:207], v[180:183], v[100:103]
	v_mfma_f32_16x16x32_bf16 v[96:99], v[212:215], v[180:183], v[96:99]
	v_mfma_f32_16x16x32_bf16 v[84:87], v[204:207], v[188:191], v[84:87]
	v_mfma_f32_16x16x32_bf16 v[80:83], v[212:215], v[188:191], v[80:83]
	v_mfma_f32_16x16x32_bf16 v[68:71], v[204:207], v[196:199], v[68:71]
	v_mfma_f32_16x16x32_bf16 v[64:67], v[212:215], v[196:199], v[64:67]
	s_mov_b32 m0, s19
	s_add_u32 s82, s28, 0x80
	s_addc_u32 s83, s29, 0
	s_barrier
	ds_read_b128 v[168:171], v149 offset:16384
	ds_read_b128 v[172:175], v149 offset:17408
	ds_read_b128 v[176:179], v149 offset:18432
	ds_read_b128 v[180:183], v149 offset:19456
	ds_read_b128 v[184:187], v149 offset:20480
	ds_read_b128 v[188:191], v149 offset:21504
	ds_read_b128 v[192:195], v149 offset:22528
	ds_read_b128 v[196:199], v149 offset:23552
	global_load_lds_dwordx4 v134, s[28:29]
	s_mov_b32 m0, s42
	s_nop 0
	global_load_lds_dwordx4 v130, s[28:29]
	s_barrier
	s_waitcnt lgkmcnt(0)
	s_waitcnt lgkmcnt(0)
	v_mfma_f32_16x16x32_bf16 v[60:63], v[152:155], v[168:171], v[60:63]
	v_mfma_f32_16x16x32_bf16 v[56:59], v[160:163], v[168:171], v[56:59]
	v_mfma_f32_16x16x32_bf16 v[44:47], v[152:155], v[176:179], v[44:47]
	v_mfma_f32_16x16x32_bf16 v[40:43], v[160:163], v[176:179], v[40:43]
	v_mfma_f32_16x16x32_bf16 v[28:31], v[152:155], v[184:187], v[28:31]
	v_mfma_f32_16x16x32_bf16 v[24:27], v[160:163], v[184:187], v[24:27]
	v_mfma_f32_16x16x32_bf16 v[12:15], v[152:155], v[192:195], v[12:15]
	v_mfma_f32_16x16x32_bf16 v[8:11], v[160:163], v[192:195], v[8:11]
	v_mfma_f32_16x16x32_bf16 v[60:63], v[156:159], v[172:175], v[60:63]
	v_mfma_f32_16x16x32_bf16 v[56:59], v[164:167], v[172:175], v[56:59]
	v_mfma_f32_16x16x32_bf16 v[44:47], v[156:159], v[180:183], v[44:47]
	v_mfma_f32_16x16x32_bf16 v[40:43], v[164:167], v[180:183], v[40:43]
	v_mfma_f32_16x16x32_bf16 v[28:31], v[156:159], v[188:191], v[28:31]
	v_mfma_f32_16x16x32_bf16 v[24:27], v[164:167], v[188:191], v[24:27]
	v_mfma_f32_16x16x32_bf16 v[12:15], v[156:159], v[196:199], v[12:15]
	v_mfma_f32_16x16x32_bf16 v[8:11], v[164:167], v[196:199], v[8:11]
	s_barrier
	s_add_u32 s58, s26, 0x40000
	s_addc_u32 s59, s27, 0
	s_add_i32 s60, s48, s31
	s_mov_b32 m0, s60
	s_nop 0
	global_load_lds_dwordx4 v132, s[58:59]
	s_add_i32 m0, s60, 0x2000
	s_nop 0
	global_load_lds_dwordx4 v128, s[58:59]
	s_waitcnt vmcnt(8)
	s_barrier
	v_mfma_f32_16x16x32_bf16 v[52:55], v[200:203], v[168:171], v[52:55]
	v_mfma_f32_16x16x32_bf16 v[48:51], v[208:211], v[168:171], v[48:51]
	v_mfma_f32_16x16x32_bf16 v[36:39], v[200:203], v[176:179], v[36:39]
	v_mfma_f32_16x16x32_bf16 v[32:35], v[208:211], v[176:179], v[32:35]
	v_mfma_f32_16x16x32_bf16 v[20:23], v[200:203], v[184:187], v[20:23]
	v_mfma_f32_16x16x32_bf16 v[16:19], v[208:211], v[184:187], v[16:19]
	v_mfma_f32_16x16x32_bf16 v[4:7], v[200:203], v[192:195], v[4:7]
	v_mfma_f32_16x16x32_bf16 v[0:3], v[208:211], v[192:195], v[0:3]
	v_mfma_f32_16x16x32_bf16 v[52:55], v[204:207], v[172:175], v[52:55]
	v_mfma_f32_16x16x32_bf16 v[48:51], v[212:215], v[172:175], v[48:51]
	v_mfma_f32_16x16x32_bf16 v[36:39], v[204:207], v[180:183], v[36:39]
	v_mfma_f32_16x16x32_bf16 v[32:35], v[212:215], v[180:183], v[32:35]
	v_mfma_f32_16x16x32_bf16 v[20:23], v[204:207], v[188:191], v[20:23]
	v_mfma_f32_16x16x32_bf16 v[16:19], v[212:215], v[188:191], v[16:19]
	v_mfma_f32_16x16x32_bf16 v[4:7], v[204:207], v[196:199], v[4:7]
	v_mfma_f32_16x16x32_bf16 v[0:3], v[212:215], v[196:199], v[0:3]
	s_add_i32 s58, 0, 0x18000
	v_add_u32_e32 v151, s58, v145
	s_barrier
.Lg893_mid:
	ds_read_b128 v[152:155], v151
	ds_read_b128 v[156:159], v151 offset:1024
	ds_read_b128 v[160:163], v151 offset:2048
	ds_read_b128 v[164:167], v151 offset:3072
	s_add_u32 s28, s28, 0x40000
	s_addc_u32 s29, s29, 0
	s_mov_b32 m0, s43
	ds_read_b128 v[168:171], v149 offset:32768
	ds_read_b128 v[172:175], v149 offset:33792
	ds_read_b128 v[176:179], v149 offset:34816
	ds_read_b128 v[180:183], v149 offset:35840
	ds_read_b128 v[184:187], v149 offset:36864
	ds_read_b128 v[188:191], v149 offset:37888
	ds_read_b128 v[192:195], v149 offset:38912
	ds_read_b128 v[196:199], v149 offset:39936
	global_load_lds_dwordx4 v134, s[28:29]
	s_mov_b32 m0, s44
	s_nop 0
	global_load_lds_dwordx4 v130, s[28:29]
	s_waitcnt lgkmcnt(8)
	s_barrier
	s_waitcnt lgkmcnt(0)
	s_waitcnt lgkmcnt(0)
	v_mfma_f32_16x16x32_bf16 v[124:127], v[152:155], v[168:171], v[124:127]
	v_mfma_f32_16x16x32_bf16 v[120:123], v[160:163], v[168:171], v[120:123]
	v_mfma_f32_16x16x32_bf16 v[108:111], v[152:155], v[176:179], v[108:111]
	v_mfma_f32_16x16x32_bf16 v[104:107], v[160:163], v[176:179], v[104:107]
	v_mfma_f32_16x16x32_bf16 v[92:95], v[152:155], v[184:187], v[92:95]
	v_mfma_f32_16x16x32_bf16 v[88:91], v[160:163], v[184:187], v[88:91]
	v_mfma_f32_16x16x32_bf16 v[76:79], v[152:155], v[192:195], v[76:79]
	v_mfma_f32_16x16x32_bf16 v[72:75], v[160:163], v[192:195], v[72:75]
	v_mfma_f32_16x16x32_bf16 v[124:127], v[156:159], v[172:175], v[124:127]
	v_mfma_f32_16x16x32_bf16 v[120:123], v[164:167], v[172:175], v[120:123]
	v_mfma_f32_16x16x32_bf16 v[108:111], v[156:159], v[180:183], v[108:111]
	v_mfma_f32_16x16x32_bf16 v[104:107], v[164:167], v[180:183], v[104:107]
	v_mfma_f32_16x16x32_bf16 v[92:95], v[156:159], v[188:191], v[92:95]
	v_mfma_f32_16x16x32_bf16 v[88:91], v[164:167], v[188:191], v[88:91]
	v_mfma_f32_16x16x32_bf16 v[76:79], v[156:159], v[196:199], v[76:79]
	v_mfma_f32_16x16x32_bf16 v[72:75], v[164:167], v[196:199], v[72:75]
	s_barrier
	s_add_i32 s28, 0, 0x1c000
	s_add_i32 s29, s58, s31
	v_add_u32_e32 v151, s28, v145
	s_mov_b32 m0, s29
	ds_read_b128 v[200:203], v151
	ds_read_b128 v[204:207], v151 offset:1024
	ds_read_b128 v[208:211], v151 offset:2048
	ds_read_b128 v[212:215], v151 offset:3072
	global_load_lds_dwordx4 v132, s[80:81]
	s_add_i32 m0, s29, 0x2000
	s_nop 0
	global_load_lds_dwordx4 v128, s[80:81]
	s_waitcnt vmcnt(10)
	s_barrier
	s_waitcnt lgkmcnt(0)
	s_waitcnt lgkmcnt(0)
	v_mfma_f32_16x16x32_bf16 v[116:119], v[200:203], v[168:171], v[116:119]
	v_mfma_f32_16x16x32_bf16 v[112:115], v[208:211], v[168:171], v[112:115]
	v_mfma_f32_16x16x32_bf16 v[100:103], v[200:203], v[176:179], v[100:103]
	v_mfma_f32_16x16x32_bf16 v[96:99], v[208:211], v[176:179], v[96:99]
	v_mfma_f32_16x16x32_bf16 v[84:87], v[200:203], v[184:187], v[84:87]
	v_mfma_f32_16x16x32_bf16 v[80:83], v[208:211], v[184:187], v[80:83]
	v_mfma_f32_16x16x32_bf16 v[68:71], v[200:203], v[192:195], v[68:71]
	v_mfma_f32_16x16x32_bf16 v[64:67], v[208:211], v[192:195], v[64:67]
	v_mfma_f32_16x16x32_bf16 v[116:119], v[204:207], v[172:175], v[116:119]
	v_mfma_f32_16x16x32_bf16 v[112:115], v[212:215], v[172:175], v[112:115]
	v_mfma_f32_16x16x32_bf16 v[100:103], v[204:207], v[180:183], v[100:103]
	v_mfma_f32_16x16x32_bf16 v[96:99], v[212:215], v[180:183], v[96:99]
	v_mfma_f32_16x16x32_bf16 v[84:87], v[204:207], v[188:191], v[84:87]
	v_mfma_f32_16x16x32_bf16 v[80:83], v[212:215], v[188:191], v[80:83]
	v_mfma_f32_16x16x32_bf16 v[68:71], v[204:207], v[196:199], v[68:71]
	v_mfma_f32_16x16x32_bf16 v[64:67], v[212:215], v[196:199], v[64:67]
	s_mov_b32 m0, s45
	s_barrier
	ds_read_b128 v[168:171], v149 offset:49152
	ds_read_b128 v[172:175], v149 offset:50176
	ds_read_b128 v[176:179], v149 offset:51200
	ds_read_b128 v[180:183], v149 offset:52224
	ds_read_b128 v[184:187], v149 offset:53248
	ds_read_b128 v[188:191], v149 offset:54272
	ds_read_b128 v[192:195], v149 offset:55296
	ds_read_b128 v[196:199], v149 offset:56320
	global_load_lds_dwordx4 v134, s[82:83]
	s_mov_b32 m0, s46
	s_nop 0
	global_load_lds_dwordx4 v130, s[82:83]
	s_barrier
	s_waitcnt lgkmcnt(0)
	s_waitcnt lgkmcnt(0)
	v_mfma_f32_16x16x32_bf16 v[60:63], v[152:155], v[168:171], v[60:63]
	v_mfma_f32_16x16x32_bf16 v[56:59], v[160:163], v[168:171], v[56:59]
	v_mfma_f32_16x16x32_bf16 v[44:47], v[152:155], v[176:179], v[44:47]
	v_mfma_f32_16x16x32_bf16 v[40:43], v[160:163], v[176:179], v[40:43]
	v_mfma_f32_16x16x32_bf16 v[28:31], v[152:155], v[184:187], v[28:31]
	v_mfma_f32_16x16x32_bf16 v[24:27], v[160:163], v[184:187], v[24:27]
	v_mfma_f32_16x16x32_bf16 v[12:15], v[152:155], v[192:195], v[12:15]
	v_mfma_f32_16x16x32_bf16 v[8:11], v[160:163], v[192:195], v[8:11]
	v_mfma_f32_16x16x32_bf16 v[60:63], v[156:159], v[172:175], v[60:63]
	v_mfma_f32_16x16x32_bf16 v[56:59], v[164:167], v[172:175], v[56:59]
	v_mfma_f32_16x16x32_bf16 v[44:47], v[156:159], v[180:183], v[44:47]
	v_mfma_f32_16x16x32_bf16 v[40:43], v[164:167], v[180:183], v[40:43]
	v_mfma_f32_16x16x32_bf16 v[28:31], v[156:159], v[188:191], v[28:31]
	v_mfma_f32_16x16x32_bf16 v[24:27], v[164:167], v[188:191], v[24:27]
	v_mfma_f32_16x16x32_bf16 v[12:15], v[156:159], v[196:199], v[12:15]
	v_mfma_f32_16x16x32_bf16 v[8:11], v[164:167], v[196:199], v[8:11]
	s_barrier
	s_add_u32 s26, s26, 0x40080
	s_addc_u32 s27, s27, 0
	s_add_i32 s28, s28, s31
	s_mov_b32 m0, s28
	s_nop 0
	global_load_lds_dwordx4 v132, s[26:27]
	s_add_i32 m0, s28, 0x2000
	s_nop 0
	global_load_lds_dwordx4 v128, s[26:27]
	s_waitcnt vmcnt(8)
	s_barrier
	v_mfma_f32_16x16x32_bf16 v[52:55], v[200:203], v[168:171], v[52:55]
	v_mfma_f32_16x16x32_bf16 v[48:51], v[208:211], v[168:171], v[48:51]
	v_mfma_f32_16x16x32_bf16 v[36:39], v[200:203], v[176:179], v[36:39]
	v_mfma_f32_16x16x32_bf16 v[32:35], v[208:211], v[176:179], v[32:35]
	v_mfma_f32_16x16x32_bf16 v[20:23], v[200:203], v[184:187], v[20:23]
	v_mfma_f32_16x16x32_bf16 v[16:19], v[208:211], v[184:187], v[16:19]
	v_mfma_f32_16x16x32_bf16 v[4:7], v[200:203], v[192:195], v[4:7]
	v_mfma_f32_16x16x32_bf16 v[0:3], v[208:211], v[192:195], v[0:3]
	v_mfma_f32_16x16x32_bf16 v[52:55], v[204:207], v[172:175], v[52:55]
	v_mfma_f32_16x16x32_bf16 v[48:51], v[212:215], v[172:175], v[48:51]
	v_mfma_f32_16x16x32_bf16 v[36:39], v[204:207], v[180:183], v[36:39]
	v_mfma_f32_16x16x32_bf16 v[32:35], v[212:215], v[180:183], v[32:35]
	v_mfma_f32_16x16x32_bf16 v[20:23], v[204:207], v[188:191], v[20:23]
	v_mfma_f32_16x16x32_bf16 v[16:19], v[212:215], v[188:191], v[16:19]
	v_mfma_f32_16x16x32_bf16 v[4:7], v[204:207], v[196:199], v[4:7]
	v_mfma_f32_16x16x32_bf16 v[0:3], v[212:215], v[196:199], v[0:3]
	s_add_i32 s57, s57, 2
	s_add_u32 s20, s20, 0x100
	s_addc_u32 s21, s21, 0
	s_add_u32 s55, s55, 0x100
	s_addc_u32 s56, s56, 0
	s_cmp_gt_u32 s57, 13
	s_barrier
	s_cbranch_scc0 .LBB0_893
	s_setprio 0
	s_cmpk_gt_u32 s30, 0xff
	s_cbranch_scc1 .Lg893_nox
	s_barrier

.LBB0_972:
	s_add_u32 s54, s22, 0x100
	s_addc_u32 s55, s23, 0
	s_mov_b32 s56, -2
	s_cmpk_lt_u32 s30, 0x100
	s_cbranch_scc1 .Lg973_noy
	s_setprio 1
	s_barrier
.Lg973_noy:
	ds_read_b128 v[146:149], v203
	ds_read_b128 v[150:153], v203 offset:1024
	ds_read_b128 v[154:157], v203 offset:2048
	ds_read_b128 v[158:161], v203 offset:3072
	s_add_u32 s22, s20, 0x100
	s_addc_u32 s23, s21, 0
	s_cmp_eq_u32 s56, 40
	s_cselect_b32 s27, s5, s23
	s_cselect_b32 s26, s4, s22
	s_cselect_b32 s25, s7, s55
	s_cselect_b32 s24, s6, s54
	s_add_i32 m0, s37, 0xc000
	ds_read_b128 v[162:165], v204
	ds_read_b128 v[166:169], v204 offset:1024
	ds_read_b128 v[170:173], v204 offset:2048
	ds_read_b128 v[174:177], v204 offset:3072
	ds_read_b128 v[178:181], v204 offset:4096
	ds_read_b128 v[182:185], v204 offset:5120
	ds_read_b128 v[186:189], v204 offset:6144
	ds_read_b128 v[190:193], v204 offset:7168
	global_load_lds_dwordx4 v138, s[20:21]
	s_add_i32 m0, s37, 0xe000
	s_nop 0
	global_load_lds_dwordx4 v140, s[20:21]
	s_waitcnt lgkmcnt(8)
	s_barrier
	s_waitcnt lgkmcnt(0)
	s_waitcnt lgkmcnt(0)
	v_mfma_f32_16x16x32_bf16 v[124:127], v[146:149], v[162:165], 0
	v_mfma_f32_16x16x32_bf16 v[120:123], v[154:157], v[162:165], 0
	v_mfma_f32_16x16x32_bf16 v[108:111], v[146:149], v[170:173], 0
	v_mfma_f32_16x16x32_bf16 v[104:107], v[154:157], v[170:173], 0
	v_mfma_f32_16x16x32_bf16 v[92:95], v[146:149], v[178:181], 0
	v_mfma_f32_16x16x32_bf16 v[88:91], v[154:157], v[178:181], 0
	v_mfma_f32_16x16x32_bf16 v[76:79], v[146:149], v[186:189], 0
	v_mfma_f32_16x16x32_bf16 v[72:75], v[154:157], v[186:189], 0
	v_mfma_f32_16x16x32_bf16 v[124:127], v[150:153], v[166:169], v[124:127]
	v_mfma_f32_16x16x32_bf16 v[120:123], v[158:161], v[166:169], v[120:123]
	v_mfma_f32_16x16x32_bf16 v[108:111], v[150:153], v[174:177], v[108:111]
	v_mfma_f32_16x16x32_bf16 v[104:107], v[158:161], v[174:177], v[104:107]
	v_mfma_f32_16x16x32_bf16 v[92:95], v[150:153], v[182:185], v[92:95]
	v_mfma_f32_16x16x32_bf16 v[88:91], v[158:161], v[182:185], v[88:91]
	v_mfma_f32_16x16x32_bf16 v[76:79], v[150:153], v[190:193], v[76:79]
	v_mfma_f32_16x16x32_bf16 v[72:75], v[158:161], v[190:193], v[72:75]
	s_barrier
	s_add_i32 s20, s47, s36
	s_add_u32 s80, s24, 0x80
	s_addc_u32 s81, s25, 0
	s_mov_b32 m0, s20
	ds_read_b128 v[194:197], v205
	ds_read_b128 v[208:211], v205 offset:1024
	ds_read_b128 v[212:215], v205 offset:2048
	ds_read_b128 v[216:219], v205 offset:3072
	global_load_lds_dwordx4 v130, s[24:25]
	s_add_i32 m0, s20, 0x2000
	s_nop 0
	global_load_lds_dwordx4 v134, s[24:25]
	s_waitcnt vmcnt(10)
	s_barrier
	s_waitcnt lgkmcnt(0)
	s_waitcnt lgkmcnt(0)
	v_mfma_f32_16x16x32_bf16 v[116:119], v[194:197], v[162:165], 0
	v_mfma_f32_16x16x32_bf16 v[112:115], v[212:215], v[162:165], 0
	v_mfma_f32_16x16x32_bf16 v[100:103], v[194:197], v[170:173], 0
	v_mfma_f32_16x16x32_bf16 v[96:99], v[212:215], v[170:173], 0
	v_mfma_f32_16x16x32_bf16 v[84:87], v[194:197], v[178:181], 0
	v_mfma_f32_16x16x32_bf16 v[80:83], v[212:215], v[178:181], 0
	v_mfma_f32_16x16x32_bf16 v[68:71], v[194:197], v[186:189], 0
	v_mfma_f32_16x16x32_bf16 v[64:67], v[212:215], v[186:189], 0
	v_mfma_f32_16x16x32_bf16 v[116:119], v[208:211], v[166:169], v[116:119]
	v_mfma_f32_16x16x32_bf16 v[112:115], v[216:219], v[166:169], v[112:115]
	v_mfma_f32_16x16x32_bf16 v[100:103], v[208:211], v[174:177], v[100:103]
	v_mfma_f32_16x16x32_bf16 v[96:99], v[216:219], v[174:177], v[96:99]
	v_mfma_f32_16x16x32_bf16 v[84:87], v[208:211], v[182:185], v[84:87]
	v_mfma_f32_16x16x32_bf16 v[80:83], v[216:219], v[182:185], v[80:83]
	v_mfma_f32_16x16x32_bf16 v[68:71], v[208:211], v[190:193], v[68:71]
	v_mfma_f32_16x16x32_bf16 v[64:67], v[216:219], v[190:193], v[64:67]
	s_mov_b32 m0, s37
	s_add_u32 s82, s26, 0x80
	s_addc_u32 s83, s27, 0
	s_barrier
	ds_read_b128 v[162:165], v204 offset:16384
	ds_read_b128 v[166:169], v204 offset:17408
	ds_read_b128 v[170:173], v204 offset:18432
	ds_read_b128 v[174:177], v204 offset:19456
	ds_read_b128 v[178:181], v204 offset:20480
	ds_read_b128 v[182:185], v204 offset:21504
	ds_read_b128 v[186:189], v204 offset:22528
	ds_read_b128 v[190:193], v204 offset:23552
	global_load_lds_dwordx4 v128, s[26:27]
	s_mov_b32 m0, s38
	s_nop 0
	global_load_lds_dwordx4 v132, s[26:27]
	s_barrier
	s_waitcnt lgkmcnt(0)
	s_waitcnt lgkmcnt(0)
	v_mfma_f32_16x16x32_bf16 v[60:63], v[146:149], v[162:165], 0
	v_mfma_f32_16x16x32_bf16 v[56:59], v[154:157], v[162:165], 0
	v_mfma_f32_16x16x32_bf16 v[44:47], v[146:149], v[170:173], 0
	v_mfma_f32_16x16x32_bf16 v[40:43], v[154:157], v[170:173], 0
	v_mfma_f32_16x16x32_bf16 v[28:31], v[146:149], v[178:181], 0
	v_mfma_f32_16x16x32_bf16 v[24:27], v[154:157], v[178:181], 0
	v_mfma_f32_16x16x32_bf16 v[12:15], v[146:149], v[186:189], 0
	v_mfma_f32_16x16x32_bf16 v[8:11], v[154:157], v[186:189], 0
	v_mfma_f32_16x16x32_bf16 v[60:63], v[150:153], v[166:169], v[60:63]
	v_mfma_f32_16x16x32_bf16 v[56:59], v[158:161], v[166:169], v[56:59]
	v_mfma_f32_16x16x32_bf16 v[44:47], v[150:153], v[174:177], v[44:47]
	v_mfma_f32_16x16x32_bf16 v[40:43], v[158:161], v[174:177], v[40:43]
	v_mfma_f32_16x16x32_bf16 v[28:31], v[150:153], v[182:185], v[28:31]
	v_mfma_f32_16x16x32_bf16 v[24:27], v[158:161], v[182:185], v[24:27]
	v_mfma_f32_16x16x32_bf16 v[12:15], v[150:153], v[190:193], v[12:15]
	v_mfma_f32_16x16x32_bf16 v[8:11], v[158:161], v[190:193], v[8:11]
	s_barrier
	s_add_u32 s20, s24, 0xb0000
	s_addc_u32 s21, s25, 0
	s_add_i32 s57, s48, s36
	s_mov_b32 m0, s57
	s_nop 0
	global_load_lds_dwordx4 v130, s[20:21]
	s_add_i32 m0, s57, 0x2000
	s_nop 0
	global_load_lds_dwordx4 v134, s[20:21]
	s_waitcnt vmcnt(8)
	s_barrier
	v_mfma_f32_16x16x32_bf16 v[52:55], v[194:197], v[162:165], 0
	v_mfma_f32_16x16x32_bf16 v[48:51], v[212:215], v[162:165], 0
	v_mfma_f32_16x16x32_bf16 v[36:39], v[194:197], v[170:173], 0
	v_mfma_f32_16x16x32_bf16 v[32:35], v[212:215], v[170:173], 0
	v_mfma_f32_16x16x32_bf16 v[20:23], v[194:197], v[178:181], 0
	v_mfma_f32_16x16x32_bf16 v[16:19], v[212:215], v[178:181], 0
	v_mfma_f32_16x16x32_bf16 v[4:7], v[194:197], v[186:189], 0
	v_mfma_f32_16x16x32_bf16 v[0:3], v[212:215], v[186:189], 0
	v_mfma_f32_16x16x32_bf16 v[52:55], v[208:211], v[166:169], v[52:55]
	v_mfma_f32_16x16x32_bf16 v[48:51], v[216:219], v[166:169], v[48:51]
	v_mfma_f32_16x16x32_bf16 v[36:39], v[208:211], v[174:177], v[36:39]
	v_mfma_f32_16x16x32_bf16 v[32:35], v[216:219], v[174:177], v[32:35]
	v_mfma_f32_16x16x32_bf16 v[20:23], v[208:211], v[182:185], v[20:23]
	v_mfma_f32_16x16x32_bf16 v[16:19], v[216:219], v[182:185], v[16:19]
	v_mfma_f32_16x16x32_bf16 v[4:7], v[208:211], v[190:193], v[4:7]
	v_mfma_f32_16x16x32_bf16 v[0:3], v[216:219], v[190:193], v[0:3]
	s_add_i32 s57, 0, 0x18000
	v_add_u32_e32 v158, s57, v201
	s_barrier
	s_branch .Lg973_mid
.LBB0_973:
	ds_read_b128 v[146:149], v203
	ds_read_b128 v[150:153], v203 offset:1024
	ds_read_b128 v[154:157], v203 offset:2048
	ds_read_b128 v[158:161], v203 offset:3072
	s_add_u32 s22, s20, 0x100
	s_addc_u32 s23, s21, 0
	s_cmp_eq_u32 s56, 40
	s_cselect_b32 s27, s5, s23
	s_cselect_b32 s26, s4, s22
	s_cselect_b32 s25, s7, s55
	s_cselect_b32 s24, s6, s54
	s_add_i32 m0, s37, 0xc000
	ds_read_b128 v[162:165], v204
	ds_read_b128 v[166:169], v204 offset:1024
	ds_read_b128 v[170:173], v204 offset:2048
	ds_read_b128 v[174:177], v204 offset:3072
	ds_read_b128 v[178:181], v204 offset:4096
	ds_read_b128 v[182:185], v204 offset:5120
	ds_read_b128 v[186:189], v204 offset:6144
	ds_read_b128 v[190:193], v204 offset:7168
	global_load_lds_dwordx4 v138, s[20:21]
	s_add_i32 m0, s37, 0xe000
	s_nop 0
	global_load_lds_dwordx4 v140, s[20:21]
	s_waitcnt lgkmcnt(8)
	s_barrier
	s_waitcnt lgkmcnt(0)
	s_waitcnt lgkmcnt(0)
	v_mfma_f32_16x16x32_bf16 v[124:127], v[146:149], v[162:165], v[124:127]
	v_mfma_f32_16x16x32_bf16 v[120:123], v[154:157], v[162:165], v[120:123]
	v_mfma_f32_16x16x32_bf16 v[108:111], v[146:149], v[170:173], v[108:111]
	v_mfma_f32_16x16x32_bf16 v[104:107], v[154:157], v[170:173], v[104:107]
	v_mfma_f32_16x16x32_bf16 v[92:95], v[146:149], v[178:181], v[92:95]
	v_mfma_f32_16x16x32_bf16 v[88:91], v[154:157], v[178:181], v[88:91]
	v_mfma_f32_16x16x32_bf16 v[76:79], v[146:149], v[186:189], v[76:79]
	v_mfma_f32_16x16x32_bf16 v[72:75], v[154:157], v[186:189], v[72:75]
	v_mfma_f32_16x16x32_bf16 v[124:127], v[150:153], v[166:169], v[124:127]
	v_mfma_f32_16x16x32_bf16 v[120:123], v[158:161], v[166:169], v[120:123]
	v_mfma_f32_16x16x32_bf16 v[108:111], v[150:153], v[174:177], v[108:111]
	v_mfma_f32_16x16x32_bf16 v[104:107], v[158:161], v[174:177], v[104:107]
	v_mfma_f32_16x16x32_bf16 v[92:95], v[150:153], v[182:185], v[92:95]
	v_mfma_f32_16x16x32_bf16 v[88:91], v[158:161], v[182:185], v[88:91]
	v_mfma_f32_16x16x32_bf16 v[76:79], v[150:153], v[190:193], v[76:79]
	v_mfma_f32_16x16x32_bf16 v[72:75], v[158:161], v[190:193], v[72:75]
	s_barrier
	s_add_i32 s20, s47, s36
	s_add_u32 s80, s24, 0x80
	s_addc_u32 s81, s25, 0
	s_mov_b32 m0, s20
	ds_read_b128 v[194:197], v205
	ds_read_b128 v[208:211], v205 offset:1024
	ds_read_b128 v[212:215], v205 offset:2048
	ds_read_b128 v[216:219], v205 offset:3072
	global_load_lds_dwordx4 v130, s[24:25]
	s_add_i32 m0, s20, 0x2000
	s_nop 0
	global_load_lds_dwordx4 v134, s[24:25]
	s_waitcnt vmcnt(10)
	s_barrier
	s_waitcnt lgkmcnt(0)
	s_waitcnt lgkmcnt(0)
	v_mfma_f32_16x16x32_bf16 v[116:119], v[194:197], v[162:165], v[116:119]
	v_mfma_f32_16x16x32_bf16 v[112:115], v[212:215], v[162:165], v[112:115]
	v_mfma_f32_16x16x32_bf16 v[100:103], v[194:197], v[170:173], v[100:103]
	v_mfma_f32_16x16x32_bf16 v[96:99], v[212:215], v[170:173], v[96:99]
	v_mfma_f32_16x16x32_bf16 v[84:87], v[194:197], v[178:181], v[84:87]
	v_mfma_f32_16x16x32_bf16 v[80:83], v[212:215], v[178:181], v[80:83]
	v_mfma_f32_16x16x32_bf16 v[68:71], v[194:197], v[186:189], v[68:71]
	v_mfma_f32_16x16x32_bf16 v[64:67], v[212:215], v[186:189], v[64:67]
	v_mfma_f32_16x16x32_bf16 v[116:119], v[208:211], v[166:169], v[116:119]
	v_mfma_f32_16x16x32_bf16 v[112:115], v[216:219], v[166:169], v[112:115]
	v_mfma_f32_16x16x32_bf16 v[100:103], v[208:211], v[174:177], v[100:103]
	v_mfma_f32_16x16x32_bf16 v[96:99], v[216:219], v[174:177], v[96:99]
	v_mfma_f32_16x16x32_bf16 v[84:87], v[208:211], v[182:185], v[84:87]
	v_mfma_f32_16x16x32_bf16 v[80:83], v[216:219], v[182:185], v[80:83]
	v_mfma_f32_16x16x32_bf16 v[68:71], v[208:211], v[190:193], v[68:71]
	v_mfma_f32_16x16x32_bf16 v[64:67], v[216:219], v[190:193], v[64:67]
	s_mov_b32 m0, s37
	s_add_u32 s82, s26, 0x80
	s_addc_u32 s83, s27, 0
	s_barrier
	ds_read_b128 v[162:165], v204 offset:16384
	ds_read_b128 v[166:169], v204 offset:17408
	ds_read_b128 v[170:173], v204 offset:18432
	ds_read_b128 v[174:177], v204 offset:19456
	ds_read_b128 v[178:181], v204 offset:20480
	ds_read_b128 v[182:185], v204 offset:21504
	ds_read_b128 v[186:189], v204 offset:22528
	ds_read_b128 v[190:193], v204 offset:23552
	global_load_lds_dwordx4 v128, s[26:27]
	s_mov_b32 m0, s38
	s_nop 0
	global_load_lds_dwordx4 v132, s[26:27]
	s_barrier
	s_waitcnt lgkmcnt(0)
	s_waitcnt lgkmcnt(0)
	v_mfma_f32_16x16x32_bf16 v[60:63], v[146:149], v[162:165], v[60:63]
	v_mfma_f32_16x16x32_bf16 v[56:59], v[154:157], v[162:165], v[56:59]
	v_mfma_f32_16x16x32_bf16 v[44:47], v[146:149], v[170:173], v[44:47]
	v_mfma_f32_16x16x32_bf16 v[40:43], v[154:157], v[170:173], v[40:43]
	v_mfma_f32_16x16x32_bf16 v[28:31], v[146:149], v[178:181], v[28:31]
	v_mfma_f32_16x16x32_bf16 v[24:27], v[154:157], v[178:181], v[24:27]
	v_mfma_f32_16x16x32_bf16 v[12:15], v[146:149], v[186:189], v[12:15]
	v_mfma_f32_16x16x32_bf16 v[8:11], v[154:157], v[186:189], v[8:11]
	v_mfma_f32_16x16x32_bf16 v[60:63], v[150:153], v[166:169], v[60:63]
	v_mfma_f32_16x16x32_bf16 v[56:59], v[158:161], v[166:169], v[56:59]
	v_mfma_f32_16x16x32_bf16 v[44:47], v[150:153], v[174:177], v[44:47]
	v_mfma_f32_16x16x32_bf16 v[40:43], v[158:161], v[174:177], v[40:43]
	v_mfma_f32_16x16x32_bf16 v[28:31], v[150:153], v[182:185], v[28:31]
	v_mfma_f32_16x16x32_bf16 v[24:27], v[158:161], v[182:185], v[24:27]
	v_mfma_f32_16x16x32_bf16 v[12:15], v[150:153], v[190:193], v[12:15]
	v_mfma_f32_16x16x32_bf16 v[8:11], v[158:161], v[190:193], v[8:11]
	s_barrier
	s_add_u32 s20, s24, 0xb0000
	s_addc_u32 s21, s25, 0
	s_add_i32 s57, s48, s36
	s_mov_b32 m0, s57
	s_nop 0
	global_load_lds_dwordx4 v130, s[20:21]
	s_add_i32 m0, s57, 0x2000
	s_nop 0
	global_load_lds_dwordx4 v134, s[20:21]
	s_waitcnt vmcnt(8)
	s_barrier
	v_mfma_f32_16x16x32_bf16 v[52:55], v[194:197], v[162:165], v[52:55]
	v_mfma_f32_16x16x32_bf16 v[48:51], v[212:215], v[162:165], v[48:51]
	v_mfma_f32_16x16x32_bf16 v[36:39], v[194:197], v[170:173], v[36:39]
	v_mfma_f32_16x16x32_bf16 v[32:35], v[212:215], v[170:173], v[32:35]
	v_mfma_f32_16x16x32_bf16 v[20:23], v[194:197], v[178:181], v[20:23]
	v_mfma_f32_16x16x32_bf16 v[16:19], v[212:215], v[178:181], v[16:19]
	v_mfma_f32_16x16x32_bf16 v[4:7], v[194:197], v[186:189], v[4:7]
	v_mfma_f32_16x16x32_bf16 v[0:3], v[212:215], v[186:189], v[0:3]
	v_mfma_f32_16x16x32_bf16 v[52:55], v[208:211], v[166:169], v[52:55]
	v_mfma_f32_16x16x32_bf16 v[48:51], v[216:219], v[166:169], v[48:51]
	v_mfma_f32_16x16x32_bf16 v[36:39], v[208:211], v[174:177], v[36:39]
	v_mfma_f32_16x16x32_bf16 v[32:35], v[216:219], v[174:177], v[32:35]
	v_mfma_f32_16x16x32_bf16 v[20:23], v[208:211], v[182:185], v[20:23]
	v_mfma_f32_16x16x32_bf16 v[16:19], v[216:219], v[182:185], v[16:19]
	v_mfma_f32_16x16x32_bf16 v[4:7], v[208:211], v[190:193], v[4:7]
	v_mfma_f32_16x16x32_bf16 v[0:3], v[216:219], v[190:193], v[0:3]
	s_add_i32 s57, 0, 0x18000
	v_add_u32_e32 v158, s57, v201
	s_barrier
.Lg973_mid:
	ds_read_b128 v[146:149], v158
	ds_read_b128 v[150:153], v158 offset:1024
	ds_read_b128 v[154:157], v158 offset:2048
	ds_read_b128 v[158:161], v158 offset:3072
	s_add_u32 s20, s26, 0xb0000
	s_addc_u32 s21, s27, 0
	s_mov_b32 m0, s39
	ds_read_b128 v[162:165], v204 offset:32768
	ds_read_b128 v[166:169], v204 offset:33792
	ds_read_b128 v[170:173], v204 offset:34816
	ds_read_b128 v[174:177], v204 offset:35840
	ds_read_b128 v[178:181], v204 offset:36864
	ds_read_b128 v[182:185], v204 offset:37888
	ds_read_b128 v[186:189], v204 offset:38912
	ds_read_b128 v[190:193], v204 offset:39936
	global_load_lds_dwordx4 v128, s[20:21]
	s_mov_b32 m0, s40
	s_nop 0
	global_load_lds_dwordx4 v132, s[20:21]
	s_waitcnt lgkmcnt(8)
	s_barrier
	s_waitcnt lgkmcnt(0)
	s_waitcnt lgkmcnt(0)
	v_mfma_f32_16x16x32_bf16 v[124:127], v[146:149], v[162:165], v[124:127]
	v_mfma_f32_16x16x32_bf16 v[120:123], v[154:157], v[162:165], v[120:123]
	v_mfma_f32_16x16x32_bf16 v[108:111], v[146:149], v[170:173], v[108:111]
	v_mfma_f32_16x16x32_bf16 v[104:107], v[154:157], v[170:173], v[104:107]
	v_mfma_f32_16x16x32_bf16 v[92:95], v[146:149], v[178:181], v[92:95]
	v_mfma_f32_16x16x32_bf16 v[88:91], v[154:157], v[178:181], v[88:91]
	v_mfma_f32_16x16x32_bf16 v[76:79], v[146:149], v[186:189], v[76:79]
	v_mfma_f32_16x16x32_bf16 v[72:75], v[154:157], v[186:189], v[72:75]
	v_mfma_f32_16x16x32_bf16 v[124:127], v[150:153], v[166:169], v[124:127]
	v_mfma_f32_16x16x32_bf16 v[120:123], v[158:161], v[166:169], v[120:123]
	v_mfma_f32_16x16x32_bf16 v[108:111], v[150:153], v[174:177], v[108:111]
	v_mfma_f32_16x16x32_bf16 v[104:107], v[158:161], v[174:177], v[104:107]
	v_mfma_f32_16x16x32_bf16 v[92:95], v[150:153], v[182:185], v[92:95]
	v_mfma_f32_16x16x32_bf16 v[88:91], v[158:161], v[182:185], v[88:91]
	v_mfma_f32_16x16x32_bf16 v[76:79], v[150:153], v[190:193], v[76:79]
	v_mfma_f32_16x16x32_bf16 v[72:75], v[158:161], v[190:193], v[72:75]
	s_barrier
	s_add_i32 s26, 0, 0x1c000
	s_add_i32 s20, s57, s36
	v_add_u32_e32 v216, s26, v201
	s_mov_b32 m0, s20
	ds_read_b128 v[194:197], v216
	ds_read_b128 v[208:211], v216 offset:1024
	ds_read_b128 v[212:215], v216 offset:2048
	ds_read_b128 v[216:219], v216 offset:3072
	global_load_lds_dwordx4 v130, s[80:81]
	s_add_i32 m0, s20, 0x2000
	s_nop 0
	global_load_lds_dwordx4 v134, s[80:81]
	s_waitcnt vmcnt(10)
	s_barrier
	s_waitcnt lgkmcnt(0)
	s_waitcnt lgkmcnt(0)
	v_mfma_f32_16x16x32_bf16 v[116:119], v[194:197], v[162:165], v[116:119]
	v_mfma_f32_16x16x32_bf16 v[112:115], v[212:215], v[162:165], v[112:115]
	v_mfma_f32_16x16x32_bf16 v[100:103], v[194:197], v[170:173], v[100:103]
	v_mfma_f32_16x16x32_bf16 v[96:99], v[212:215], v[170:173], v[96:99]
	v_mfma_f32_16x16x32_bf16 v[84:87], v[194:197], v[178:181], v[84:87]
	v_mfma_f32_16x16x32_bf16 v[80:83], v[212:215], v[178:181], v[80:83]
	v_mfma_f32_16x16x32_bf16 v[68:71], v[194:197], v[186:189], v[68:71]
	v_mfma_f32_16x16x32_bf16 v[64:67], v[212:215], v[186:189], v[64:67]
	v_mfma_f32_16x16x32_bf16 v[116:119], v[208:211], v[166:169], v[116:119]
	v_mfma_f32_16x16x32_bf16 v[112:115], v[216:219], v[166:169], v[112:115]
	v_mfma_f32_16x16x32_bf16 v[100:103], v[208:211], v[174:177], v[100:103]
	v_mfma_f32_16x16x32_bf16 v[96:99], v[216:219], v[174:177], v[96:99]
	v_mfma_f32_16x16x32_bf16 v[84:87], v[208:211], v[182:185], v[84:87]
	v_mfma_f32_16x16x32_bf16 v[80:83], v[216:219], v[182:185], v[80:83]
	v_mfma_f32_16x16x32_bf16 v[68:71], v[208:211], v[190:193], v[68:71]
	v_mfma_f32_16x16x32_bf16 v[64:67], v[216:219], v[190:193], v[64:67]
	s_mov_b32 m0, s42
	s_barrier
	ds_read_b128 v[162:165], v204 offset:49152
	ds_read_b128 v[166:169], v204 offset:50176
	ds_read_b128 v[170:173], v204 offset:51200
	ds_read_b128 v[174:177], v204 offset:52224
	ds_read_b128 v[178:181], v204 offset:53248
	ds_read_b128 v[182:185], v204 offset:54272
	ds_read_b128 v[186:189], v204 offset:55296
	ds_read_b128 v[190:193], v204 offset:56320
	global_load_lds_dwordx4 v128, s[82:83]
	s_mov_b32 m0, s43
	s_nop 0
	global_load_lds_dwordx4 v132, s[82:83]
	s_barrier
	s_waitcnt lgkmcnt(0)
	s_waitcnt lgkmcnt(0)
	v_mfma_f32_16x16x32_bf16 v[60:63], v[146:149], v[162:165], v[60:63]
	v_mfma_f32_16x16x32_bf16 v[56:59], v[154:157], v[162:165], v[56:59]
	v_mfma_f32_16x16x32_bf16 v[44:47], v[146:149], v[170:173], v[44:47]
	v_mfma_f32_16x16x32_bf16 v[40:43], v[154:157], v[170:173], v[40:43]
	v_mfma_f32_16x16x32_bf16 v[28:31], v[146:149], v[178:181], v[28:31]
	v_mfma_f32_16x16x32_bf16 v[24:27], v[154:157], v[178:181], v[24:27]
	v_mfma_f32_16x16x32_bf16 v[12:15], v[146:149], v[186:189], v[12:15]
	v_mfma_f32_16x16x32_bf16 v[8:11], v[154:157], v[186:189], v[8:11]
	v_mfma_f32_16x16x32_bf16 v[60:63], v[150:153], v[166:169], v[60:63]
	v_mfma_f32_16x16x32_bf16 v[56:59], v[158:161], v[166:169], v[56:59]
	v_mfma_f32_16x16x32_bf16 v[44:47], v[150:153], v[174:177], v[44:47]
	v_mfma_f32_16x16x32_bf16 v[40:43], v[158:161], v[174:177], v[40:43]
	v_mfma_f32_16x16x32_bf16 v[28:31], v[150:153], v[182:185], v[28:31]
	v_mfma_f32_16x16x32_bf16 v[24:27], v[158:161], v[182:185], v[24:27]
	v_mfma_f32_16x16x32_bf16 v[12:15], v[150:153], v[190:193], v[12:15]
	v_mfma_f32_16x16x32_bf16 v[8:11], v[158:161], v[190:193], v[8:11]
	s_barrier
	s_add_u32 s20, s24, 0xb0080
	s_addc_u32 s21, s25, 0
	s_add_i32 s24, s26, s36
	s_mov_b32 m0, s24
	s_nop 0
	global_load_lds_dwordx4 v130, s[20:21]
	s_add_i32 m0, s24, 0x2000
	s_nop 0
	global_load_lds_dwordx4 v134, s[20:21]
	s_waitcnt vmcnt(8)
	s_barrier
	v_mfma_f32_16x16x32_bf16 v[52:55], v[194:197], v[162:165], v[52:55]
	v_mfma_f32_16x16x32_bf16 v[48:51], v[212:215], v[162:165], v[48:51]
	v_mfma_f32_16x16x32_bf16 v[36:39], v[194:197], v[170:173], v[36:39]
	v_mfma_f32_16x16x32_bf16 v[32:35], v[212:215], v[170:173], v[32:35]
	v_mfma_f32_16x16x32_bf16 v[20:23], v[194:197], v[178:181], v[20:23]
	v_mfma_f32_16x16x32_bf16 v[16:19], v[212:215], v[178:181], v[16:19]
	v_mfma_f32_16x16x32_bf16 v[4:7], v[194:197], v[186:189], v[4:7]
	v_mfma_f32_16x16x32_bf16 v[0:3], v[212:215], v[186:189], v[0:3]
	v_mfma_f32_16x16x32_bf16 v[52:55], v[208:211], v[166:169], v[52:55]
	v_mfma_f32_16x16x32_bf16 v[48:51], v[216:219], v[166:169], v[48:51]
	v_mfma_f32_16x16x32_bf16 v[36:39], v[208:211], v[174:177], v[36:39]
	v_mfma_f32_16x16x32_bf16 v[32:35], v[216:219], v[174:177], v[32:35]
	v_mfma_f32_16x16x32_bf16 v[20:23], v[208:211], v[182:185], v[20:23]
	v_mfma_f32_16x16x32_bf16 v[16:19], v[216:219], v[182:185], v[16:19]
	v_mfma_f32_16x16x32_bf16 v[4:7], v[208:211], v[190:193], v[4:7]
	v_mfma_f32_16x16x32_bf16 v[0:3], v[216:219], v[190:193], v[0:3]
	s_add_i32 s56, s56, 2
	s_add_u32 s54, s54, 0x100
	s_addc_u32 s55, s55, 0
	s_cmp_gt_u32 s56, 41
	s_mov_b64 s[20:21], s[22:23]
	s_barrier
	s_cbranch_scc0 .LBB0_973
	s_setprio 0
	s_cmpk_gt_u32 s30, 0xff
	s_cbranch_scc1 .Lg973_nox
	s_barrier
